# GEMM consumer: first K-step of each unit peeled (MFMAs start from C=0, no zero-fragment MFMAs, no accumulator zeroing)
# speedup vs baseline: 1.1500x; 1.0019x over previous
; template <int EPI>
; __device__ __forceinline__ void gemm_phase(const Params& p, const u16* __restrict__ A, int lda, const u16* __restrict__ BT, int ldb,
;                            int K, int N, u16* __restrict__ outb, int ldo, int resid_in, int boff) {
;   constexpr int LS = 72;
;   constexpr int SA = 256 * LS, SB = 128 * LS, STG = SA + SB;
;   u16* sm = (u16*)smem;
;   float* sRs = (float*)(sm + 2 * STG);
;   const int tid = threadIdx.x, lane = tid & 63, wave = tid >> 6;
;   const int wm = wave >> 1, wn = wave & 1;
;   const int lrow = tid >> 3, lch = tid & 7;
;   const int NT = N / 128;
;   const int tiles = (MT / 256) * NT;
;   const int KTALL = K / 64;
;   float* part = (float*)(p.ws + O_PART);
;   int bstart = (int)blockIdx.x - boff;
;   if (bstart < 0) bstart += gridDim.x;
;   const size_t a64 = (size_t)64 * lda, b64 = (size_t)64 * ldb;
;   const int G = gridDim.x;
.Lgm_common:
	s_add_u32 s14, s96, 0x2e00100
	s_addc_u32 s15, s97, 0
	v_mov_b32_e32 v190, 0x1c040
	ds_read_b64 v[192:193], v190
	v_lshrrev_b32_e32 v191, 6, v128
	s_waitcnt lgkmcnt(0)
	v_readfirstlane_b32 s98, v192
	v_readfirstlane_b32 s99, v193
	v_readfirstlane_b32 s4, v191
	v_readlane_b32 s5, v254, 0
	s_nop 3
	s_cmp_ge_u32 s4, 4
	s_cbranch_scc1 .Lgm_producer
	v_and_b32_e32 v240, 63, v128
	v_lshrrev_b32_e32 v249, 4, v240
	v_and_b32_e32 v248, 15, v240
	v_bfe_u32 v238, v240, 1, 3
	v_lshlrev_b32_e32 v239, 7, v248
	s_lshl_b32 s8, s4, 13
	v_or_b32_e32 v241, 0, v249
	v_xor_b32_e32 v241, v241, v238
	v_lshlrev_b32_e32 v241, 4, v241
	v_add_u32_e32 v241, v241, v239
	v_add_u32_e32 v226, s8, v241
	v_add_u32_e32 v228, 0x8000, v241
	v_or_b32_e32 v241, 4, v249
	v_xor_b32_e32 v241, v241, v238
	v_lshlrev_b32_e32 v241, 4, v241
	v_add_u32_e32 v241, v241, v239
	v_add_u32_e32 v227, s8, v241
	v_add_u32_e32 v229, 0x8000, v241
	v_lshlrev_b32_e32 v242, 2, v248
	s_lshl_b32 s10, s4, 8
	s_add_u32 s10, s10, 0x24000
	v_add_u32_e32 v242, s10, v242
	s_mov_b32 s13, 0
	s_mov_b32 s31, 0xc000
	s_mov_b32 s35, 0xc000
	s_mov_b32 s34, 0xfffe8000
	s_mov_b32 s33, 0
	s_waitcnt lgkmcnt(0)
	s_barrier

; #define RAW_BARRIER() do { asm volatile("s_waitcnt lgkmcnt(0)" ::: "memory"); __builtin_amdgcn_s_barrier(); asm volatile("" ::: "memory"); } while (0)
; template <int EPI>
; __device__ __forceinline__ void gemm_phase(const Params& p, const u16* __restrict__ A, int lda, const u16* __restrict__ BT, int ldb,
;                            int K, int N, u16* __restrict__ outb, int ldo, int resid_in, int boff) {
;     ...
;     LOADX(0);
;     if (KT > 1) LOADY(1);
;     f32x16 acc00, acc01, acc10, acc11;
;     if (EPI == EPI_RES && !part_unit) {
;       const int cc0 = n0 + wn * 64 + (lane & 31);
;       float* xfq = p.out;
; #pragma unroll
;       for (int i = 0; i < 16; i++) {
;         const int row = m0 + wm * 64 + 4 * (lane >> 5) + (i & 3) + 8 * (i >> 2);
;         const float* ra = resid_in ? xrow(p, row) : (xfq + (size_t)row * 1024);
;         const float* rb = resid_in ? xrow(p, row + 32) : (xfq + (size_t)(row + 32) * 1024);
;         acc00[i] = ra[cc0]; acc01[i] = ra[cc0 + 32];
;         acc10[i] = rb[cc0]; acc11[i] = rb[cc0 + 32];
;       }
;     } else {
; #pragma unroll
;       for (int i = 0; i < 16; i++) { acc00[i] = 0.f; acc01[i] = 0.f; acc10[i] = 0.f; acc11[i] = 0.f; }
;     }
;     float4 pq0 = make_float4(0.f, 0.f, 0.f, 0.f), pq1 = pq0, pq2 = pq0, pq3 = pq0;
;     if (EPI == EPI_SCALE || EPI == EPI_FF1) {
;       const float4* pp = (const float4*)(part + (size_t)(m0 + (tid & 255)) * 16);
;       pq0 = pp[0]; pq1 = pp[1]; pq2 = pp[2]; pq3 = pp[3];
;     }
;     __syncthreads();
;     WRITEX(0);
;     if (KT > 2) LOADX(2);
;     RAW_BARRIER();
;     for (int kt = 0; kt < KT; kt += 2) {
;       if (kt + 1 < KT) WRITEY(1);
;       if (kt + 3 < KT) LOADY(kt + 3);
;       COMPUTE(0);
;       RAW_BARRIER();
;       if (kt + 1 >= KT) break;
;       if (kt + 2 < KT) WRITEX(0);
;       if (kt + 4 < KT) LOADX(kt + 4);
;       COMPUTE(1);
;       RAW_BARRIER();
;     }
.Lgm_dec_done_c:
	s_sub_u32 s18, s9, 1
	s_cmp_eq_u32 s10, 1
	s_cbranch_scc1 .Lgc_unitN
	ds_read_b128 v[130:133], v226
	ds_read_b128 v[146:149], v228
	ds_read_b128 v[150:153], v228 offset:2048
	ds_read_b128 v[154:157], v228 offset:4096
	ds_read_b128 v[158:161], v228 offset:6144
	ds_read_b128 v[162:165], v228 offset:8192
	ds_read_b128 v[166:169], v228 offset:10240
	ds_read_b128 v[170:173], v228 offset:12288
	ds_read_b128 v[174:177], v228 offset:14336
	ds_read_b128 v[134:137], v226 offset:2048
	ds_read_b128 v[138:141], v226 offset:4096
	ds_read_b128 v[142:145], v226 offset:6144
	s_waitcnt lgkmcnt(3)
	v_mfma_f32_16x16x32_bf16 v[0:3], v[146:149], v[130:133], 0
	ds_read_b128 v[178:181], v227
	v_mfma_f32_16x16x32_bf16 v[4:7], v[150:153], v[130:133], 0
	ds_read_b128 v[194:197], v229
	v_mfma_f32_16x16x32_bf16 v[8:11], v[154:157], v[130:133], 0
	ds_read_b128 v[198:201], v229 offset:2048
	v_mfma_f32_16x16x32_bf16 v[12:15], v[158:161], v[130:133], 0
	ds_read_b128 v[202:205], v229 offset:4096
	v_mfma_f32_16x16x32_bf16 v[16:19], v[162:165], v[130:133], 0
	ds_read_b128 v[206:209], v229 offset:6144
	v_mfma_f32_16x16x32_bf16 v[20:23], v[166:169], v[130:133], 0
	ds_read_b128 v[210:213], v229 offset:8192
	v_mfma_f32_16x16x32_bf16 v[24:27], v[170:173], v[130:133], 0
	ds_read_b128 v[214:217], v229 offset:10240
	v_mfma_f32_16x16x32_bf16 v[28:31], v[174:177], v[130:133], 0
	ds_read_b128 v[218:221], v229 offset:12288
	s_waitcnt lgkmcnt(10)
	v_mfma_f32_16x16x32_bf16 v[32:35], v[146:149], v[134:137], 0
	ds_read_b128 v[222:225], v229 offset:14336
	v_mfma_f32_16x16x32_bf16 v[36:39], v[150:153], v[134:137], 0
	ds_read_b128 v[182:185], v227 offset:2048
	v_mfma_f32_16x16x32_bf16 v[40:43], v[154:157], v[134:137], 0
	ds_read_b128 v[186:189], v227 offset:4096
	v_mfma_f32_16x16x32_bf16 v[44:47], v[158:161], v[134:137], 0
	ds_read_b128 v[190:193], v227 offset:6144
	v_mfma_f32_16x16x32_bf16 v[48:51], v[162:165], v[134:137], 0
	v_add_u32_e32 v226, s31, v226
	v_mfma_f32_16x16x32_bf16 v[52:55], v[166:169], v[134:137], 0
	v_add_u32_e32 v227, s31, v227
	v_mfma_f32_16x16x32_bf16 v[56:59], v[170:173], v[134:137], 0
	v_add_u32_e32 v228, s31, v228
	v_mfma_f32_16x16x32_bf16 v[60:63], v[174:177], v[134:137], 0
	v_add_u32_e32 v229, s31, v229
	s_waitcnt lgkmcnt(13)
	v_mfma_f32_16x16x32_bf16 v[64:67], v[146:149], v[138:141], 0
	v_mfma_f32_16x16x32_bf16 v[68:71], v[150:153], v[138:141], 0
	v_mfma_f32_16x16x32_bf16 v[72:75], v[154:157], v[138:141], 0
	v_mfma_f32_16x16x32_bf16 v[76:79], v[158:161], v[138:141], 0
	v_mfma_f32_16x16x32_bf16 v[80:83], v[162:165], v[138:141], 0
	v_mfma_f32_16x16x32_bf16 v[84:87], v[166:169], v[138:141], 0
	v_mfma_f32_16x16x32_bf16 v[88:91], v[170:173], v[138:141], 0
	v_mfma_f32_16x16x32_bf16 v[92:95], v[174:177], v[138:141], 0
	s_waitcnt lgkmcnt(12)
	v_mfma_f32_16x16x32_bf16 v[96:99], v[146:149], v[142:145], 0
	v_mfma_f32_16x16x32_bf16 v[100:103], v[150:153], v[142:145], 0
	v_mfma_f32_16x16x32_bf16 v[104:107], v[154:157], v[142:145], 0
	v_mfma_f32_16x16x32_bf16 v[108:111], v[158:161], v[142:145], 0
	v_mfma_f32_16x16x32_bf16 v[112:115], v[162:165], v[142:145], 0
	v_mfma_f32_16x16x32_bf16 v[116:119], v[166:169], v[142:145], 0
	v_mfma_f32_16x16x32_bf16 v[120:123], v[170:173], v[142:145], 0
	v_mfma_f32_16x16x32_bf16 v[124:127], v[174:177], v[142:145], 0
	s_add_u32 s13, s13, 1
	s_cmp_eq_u32 s13, 3
	s_cselect_b32 s13, 0, s13
	s_cmp_eq_u32 s13, 2
	s_cselect_b32 s31, s34, s35
	s_waitcnt lgkmcnt(0)
	s_barrier
	s_cmp_eq_u32 s18, 0
	s_cbranch_scc1 .Lgc_tailT
.Lgc_loopT:
	v_mfma_f32_16x16x32_bf16 v[0:3], v[194:197], v[178:181], v[0:3]
	ds_read_b128 v[130:133], v226
	v_mfma_f32_16x16x32_bf16 v[4:7], v[198:201], v[178:181], v[4:7]
	ds_read_b128 v[146:149], v228
	v_mfma_f32_16x16x32_bf16 v[8:11], v[202:205], v[178:181], v[8:11]
	ds_read_b128 v[150:153], v228 offset:2048
	v_mfma_f32_16x16x32_bf16 v[12:15], v[206:209], v[178:181], v[12:15]
	ds_read_b128 v[154:157], v228 offset:4096
	v_mfma_f32_16x16x32_bf16 v[16:19], v[210:213], v[178:181], v[16:19]
	ds_read_b128 v[158:161], v228 offset:6144
	v_mfma_f32_16x16x32_bf16 v[20:23], v[214:217], v[178:181], v[20:23]
	ds_read_b128 v[162:165], v228 offset:8192
	v_mfma_f32_16x16x32_bf16 v[24:27], v[218:221], v[178:181], v[24:27]
	ds_read_b128 v[166:169], v228 offset:10240
	v_mfma_f32_16x16x32_bf16 v[28:31], v[222:225], v[178:181], v[28:31]
	ds_read_b128 v[170:173], v228 offset:12288
	v_mfma_f32_16x16x32_bf16 v[32:35], v[194:197], v[182:185], v[32:35]
	ds_read_b128 v[174:177], v228 offset:14336
	v_mfma_f32_16x16x32_bf16 v[36:39], v[198:201], v[182:185], v[36:39]
	ds_read_b128 v[134:137], v226 offset:2048
	v_mfma_f32_16x16x32_bf16 v[40:43], v[202:205], v[182:185], v[40:43]
	ds_read_b128 v[138:141], v226 offset:4096
	v_mfma_f32_16x16x32_bf16 v[44:47], v[206:209], v[182:185], v[44:47]
	ds_read_b128 v[142:145], v226 offset:6144
	v_mfma_f32_16x16x32_bf16 v[48:51], v[210:213], v[182:185], v[48:51]
	v_mfma_f32_16x16x32_bf16 v[52:55], v[214:217], v[182:185], v[52:55]
	v_mfma_f32_16x16x32_bf16 v[56:59], v[218:221], v[182:185], v[56:59]
	v_mfma_f32_16x16x32_bf16 v[60:63], v[222:225], v[182:185], v[60:63]
	v_mfma_f32_16x16x32_bf16 v[64:67], v[194:197], v[186:189], v[64:67]
	v_mfma_f32_16x16x32_bf16 v[68:71], v[198:201], v[186:189], v[68:71]
	v_mfma_f32_16x16x32_bf16 v[72:75], v[202:205], v[186:189], v[72:75]
	v_mfma_f32_16x16x32_bf16 v[76:79], v[206:209], v[186:189], v[76:79]
	v_mfma_f32_16x16x32_bf16 v[80:83], v[210:213], v[186:189], v[80:83]
	v_mfma_f32_16x16x32_bf16 v[84:87], v[214:217], v[186:189], v[84:87]
	v_mfma_f32_16x16x32_bf16 v[88:91], v[218:221], v[186:189], v[88:91]
	v_mfma_f32_16x16x32_bf16 v[92:95], v[222:225], v[186:189], v[92:95]
	v_mfma_f32_16x16x32_bf16 v[96:99], v[194:197], v[190:193], v[96:99]
	v_mfma_f32_16x16x32_bf16 v[100:103], v[198:201], v[190:193], v[100:103]
	v_mfma_f32_16x16x32_bf16 v[104:107], v[202:205], v[190:193], v[104:107]
	v_mfma_f32_16x16x32_bf16 v[108:111], v[206:209], v[190:193], v[108:111]
	v_mfma_f32_16x16x32_bf16 v[112:115], v[210:213], v[190:193], v[112:115]
	v_mfma_f32_16x16x32_bf16 v[116:119], v[214:217], v[190:193], v[116:119]
	v_mfma_f32_16x16x32_bf16 v[120:123], v[218:221], v[190:193], v[120:123]
	v_mfma_f32_16x16x32_bf16 v[124:127], v[222:225], v[190:193], v[124:127]
	s_waitcnt lgkmcnt(0)
; #define RAW_BARRIER() do { asm volatile("s_waitcnt lgkmcnt(0)" ::: "memory"); __builtin_amdgcn_s_barrier(); asm volatile("" ::: "memory"); } while (0)
; template <int EPI>
; __device__ __forceinline__ void gemm_phase(const Params& p, const u16* __restrict__ A, int lda, const u16* __restrict__ BT, int ldb,
;                            int K, int N, u16* __restrict__ outb, int ldo, int resid_in, int boff) {
;     ...
;     LOADX(0);
;     if (KT > 1) LOADY(1);
;     f32x16 acc00, acc01, acc10, acc11;
;     if (EPI == EPI_RES && !part_unit) {
;       const int cc0 = n0 + wn * 64 + (lane & 31);
;       float* xfq = p.out;
; #pragma unroll
;       for (int i = 0; i < 16; i++) {
;         const int row = m0 + wm * 64 + 4 * (lane >> 5) + (i & 3) + 8 * (i >> 2);
;         const float* ra = resid_in ? xrow(p, row) : (xfq + (size_t)row * 1024);
;         const float* rb = resid_in ? xrow(p, row + 32) : (xfq + (size_t)(row + 32) * 1024);
;         acc00[i] = ra[cc0]; acc01[i] = ra[cc0 + 32];
;         acc10[i] = rb[cc0]; acc11[i] = rb[cc0 + 32];
;       }
;     } else {
; #pragma unroll
;       for (int i = 0; i < 16; i++) { acc00[i] = 0.f; acc01[i] = 0.f; acc10[i] = 0.f; acc11[i] = 0.f; }
;     }
;     float4 pq0 = make_float4(0.f, 0.f, 0.f, 0.f), pq1 = pq0, pq2 = pq0, pq3 = pq0;
;     if (EPI == EPI_SCALE || EPI == EPI_FF1) {
;       const float4* pp = (const float4*)(part + (size_t)(m0 + (tid & 255)) * 16);
;       pq0 = pp[0]; pq1 = pp[1]; pq2 = pp[2]; pq3 = pp[3];
;     }
;     __syncthreads();
;     WRITEX(0);
;     if (KT > 2) LOADX(2);
;     RAW_BARRIER();
;     for (int kt = 0; kt < KT; kt += 2) {
;       if (kt + 1 < KT) WRITEY(1);
;       if (kt + 3 < KT) LOADY(kt + 3);
;       COMPUTE(0);
;       RAW_BARRIER();
;       if (kt + 1 >= KT) break;
;       if (kt + 2 < KT) WRITEX(0);
;       if (kt + 4 < KT) LOADX(kt + 4);
;       COMPUTE(1);
;       RAW_BARRIER();
;     }
	s_nop 0
	v_mfma_f32_16x16x32_bf16 v[0:3], v[146:149], v[130:133], v[0:3]
	ds_read_b128 v[178:181], v227
	v_mfma_f32_16x16x32_bf16 v[4:7], v[150:153], v[130:133], v[4:7]
	ds_read_b128 v[194:197], v229
	v_mfma_f32_16x16x32_bf16 v[8:11], v[154:157], v[130:133], v[8:11]
	ds_read_b128 v[198:201], v229 offset:2048
	v_mfma_f32_16x16x32_bf16 v[12:15], v[158:161], v[130:133], v[12:15]
	ds_read_b128 v[202:205], v229 offset:4096
	v_mfma_f32_16x16x32_bf16 v[16:19], v[162:165], v[130:133], v[16:19]
	ds_read_b128 v[206:209], v229 offset:6144
	v_mfma_f32_16x16x32_bf16 v[20:23], v[166:169], v[130:133], v[20:23]
	ds_read_b128 v[210:213], v229 offset:8192
	v_mfma_f32_16x16x32_bf16 v[24:27], v[170:173], v[130:133], v[24:27]
	ds_read_b128 v[214:217], v229 offset:10240
	v_mfma_f32_16x16x32_bf16 v[28:31], v[174:177], v[130:133], v[28:31]
	ds_read_b128 v[218:221], v229 offset:12288
	v_mfma_f32_16x16x32_bf16 v[32:35], v[146:149], v[134:137], v[32:35]
	ds_read_b128 v[222:225], v229 offset:14336
	v_mfma_f32_16x16x32_bf16 v[36:39], v[150:153], v[134:137], v[36:39]
	ds_read_b128 v[182:185], v227 offset:2048
	v_mfma_f32_16x16x32_bf16 v[40:43], v[154:157], v[134:137], v[40:43]
	ds_read_b128 v[186:189], v227 offset:4096
	v_mfma_f32_16x16x32_bf16 v[44:47], v[158:161], v[134:137], v[44:47]
	ds_read_b128 v[190:193], v227 offset:6144
	v_mfma_f32_16x16x32_bf16 v[48:51], v[162:165], v[134:137], v[48:51]
	v_add_u32_e32 v226, s31, v226
	v_mfma_f32_16x16x32_bf16 v[52:55], v[166:169], v[134:137], v[52:55]
	v_add_u32_e32 v227, s31, v227
	v_mfma_f32_16x16x32_bf16 v[56:59], v[170:173], v[134:137], v[56:59]
	v_add_u32_e32 v228, s31, v228
	v_mfma_f32_16x16x32_bf16 v[60:63], v[174:177], v[134:137], v[60:63]
	v_add_u32_e32 v229, s31, v229
	v_mfma_f32_16x16x32_bf16 v[64:67], v[146:149], v[138:141], v[64:67]
	v_mfma_f32_16x16x32_bf16 v[68:71], v[150:153], v[138:141], v[68:71]
	v_mfma_f32_16x16x32_bf16 v[72:75], v[154:157], v[138:141], v[72:75]
	v_mfma_f32_16x16x32_bf16 v[76:79], v[158:161], v[138:141], v[76:79]
	v_mfma_f32_16x16x32_bf16 v[80:83], v[162:165], v[138:141], v[80:83]
	v_mfma_f32_16x16x32_bf16 v[84:87], v[166:169], v[138:141], v[84:87]
	v_mfma_f32_16x16x32_bf16 v[88:91], v[170:173], v[138:141], v[88:91]
	v_mfma_f32_16x16x32_bf16 v[92:95], v[174:177], v[138:141], v[92:95]
	v_mfma_f32_16x16x32_bf16 v[96:99], v[146:149], v[142:145], v[96:99]
	v_mfma_f32_16x16x32_bf16 v[100:103], v[150:153], v[142:145], v[100:103]
	v_mfma_f32_16x16x32_bf16 v[104:107], v[154:157], v[142:145], v[104:107]
	v_mfma_f32_16x16x32_bf16 v[108:111], v[158:161], v[142:145], v[108:111]
	v_mfma_f32_16x16x32_bf16 v[112:115], v[162:165], v[142:145], v[112:115]
	v_mfma_f32_16x16x32_bf16 v[116:119], v[166:169], v[142:145], v[116:119]
	v_mfma_f32_16x16x32_bf16 v[120:123], v[170:173], v[142:145], v[120:123]
	v_mfma_f32_16x16x32_bf16 v[124:127], v[174:177], v[142:145], v[124:127]
	s_add_u32 s13, s13, 1
	s_cmp_eq_u32 s13, 3
	s_cselect_b32 s13, 0, s13
	s_cmp_eq_u32 s13, 2
	s_cselect_b32 s31, s34, s35
	s_waitcnt lgkmcnt(0)
	s_barrier
	s_sub_u32 s18, s18, 1
	s_cmp_lg_u32 s18, 0
	s_cbranch_scc1 .Lgc_loopT
.Lgc_tailT:
	v_mfma_f32_16x16x32_bf16 v[0:3], v[194:197], v[178:181], v[0:3]
	v_mfma_f32_16x16x32_bf16 v[4:7], v[198:201], v[178:181], v[4:7]
	v_mfma_f32_16x16x32_bf16 v[8:11], v[202:205], v[178:181], v[8:11]
	v_mfma_f32_16x16x32_bf16 v[12:15], v[206:209], v[178:181], v[12:15]
	v_mfma_f32_16x16x32_bf16 v[16:19], v[210:213], v[178:181], v[16:19]
	v_mfma_f32_16x16x32_bf16 v[20:23], v[214:217], v[178:181], v[20:23]
	v_mfma_f32_16x16x32_bf16 v[24:27], v[218:221], v[178:181], v[24:27]
	v_mfma_f32_16x16x32_bf16 v[28:31], v[222:225], v[178:181], v[28:31]
	v_mfma_f32_16x16x32_bf16 v[32:35], v[194:197], v[182:185], v[32:35]
	v_mfma_f32_16x16x32_bf16 v[36:39], v[198:201], v[182:185], v[36:39]
	v_mfma_f32_16x16x32_bf16 v[40:43], v[202:205], v[182:185], v[40:43]
	v_mfma_f32_16x16x32_bf16 v[44:47], v[206:209], v[182:185], v[44:47]
	v_mfma_f32_16x16x32_bf16 v[48:51], v[210:213], v[182:185], v[48:51]
	v_mfma_f32_16x16x32_bf16 v[52:55], v[214:217], v[182:185], v[52:55]
	v_mfma_f32_16x16x32_bf16 v[56:59], v[218:221], v[182:185], v[56:59]
	v_mfma_f32_16x16x32_bf16 v[60:63], v[222:225], v[182:185], v[60:63]
	v_mfma_f32_16x16x32_bf16 v[64:67], v[194:197], v[186:189], v[64:67]
	v_mfma_f32_16x16x32_bf16 v[68:71], v[198:201], v[186:189], v[68:71]
	v_mfma_f32_16x16x32_bf16 v[72:75], v[202:205], v[186:189], v[72:75]
	v_mfma_f32_16x16x32_bf16 v[76:79], v[206:209], v[186:189], v[76:79]
	v_mfma_f32_16x16x32_bf16 v[80:83], v[210:213], v[186:189], v[80:83]
	v_mfma_f32_16x16x32_bf16 v[84:87], v[214:217], v[186:189], v[84:87]
	v_mfma_f32_16x16x32_bf16 v[88:91], v[218:221], v[186:189], v[88:91]
	v_mfma_f32_16x16x32_bf16 v[92:95], v[222:225], v[186:189], v[92:95]
	v_mfma_f32_16x16x32_bf16 v[96:99], v[194:197], v[190:193], v[96:99]
	v_mfma_f32_16x16x32_bf16 v[100:103], v[198:201], v[190:193], v[100:103]
	v_mfma_f32_16x16x32_bf16 v[104:107], v[202:205], v[190:193], v[104:107]
	v_mfma_f32_16x16x32_bf16 v[108:111], v[206:209], v[190:193], v[108:111]
	v_mfma_f32_16x16x32_bf16 v[112:115], v[210:213], v[190:193], v[112:115]
	v_mfma_f32_16x16x32_bf16 v[116:119], v[214:217], v[190:193], v[116:119]
	v_mfma_f32_16x16x32_bf16 v[120:123], v[218:221], v[190:193], v[120:123]
	v_mfma_f32_16x16x32_bf16 v[124:127], v[222:225], v[190:193], v[124:127]
	s_cmp_eq_u32 s30, 3
	s_cbranch_scc1 .Lgc_epi_res
; template <int EPI> ...
;     ...
;     if (EPI == EPI_SCALE || EPI == EPI_PLAIN || EPI == EPI_FF1) {
; #pragma unroll
;       for (int i = 0; i < 16; i++) {
;         const int rl = rbase + (i & 3) + 8 * (i >> 2);
;         const int row = m0 + rl;
;         float v0 = acc0[i], v1 = acc1[i];
;         if (EPI != EPI_PLAIN) { float rs = sRs[rl]; v0 *= rs; v1 *= rs; }
;         if (EPI == EPI_FF1) { v0 = fmaxf(v0, 0.f); v1 = fmaxf(v1, 0.f); v0 *= v0; v1 *= v1; }
;         outb[(size_t)row * ldo + c0] = f2bf(v0);
;         outb[(size_t)row * ldo + c1] = f2bf(v1);
;       }
; template <int EPI>
; __device__ __forceinline__ void gemm_phase(const Params& p, const u16* __restrict__ A, int lda, const u16* __restrict__ BT, int ldb,
;                            int K, int N, u16* __restrict__ outb, int ldo, int resid_in, int boff) {
;     ...
;     if (EPI == EPI_SCALE || EPI == EPI_FF1) {
;       if (tid < 256) {
;         const float sq = (pq0.x + pq0.y + pq0.z + pq0.w) + (pq1.x + pq1.y + pq1.z + pq1.w) + (pq2.x + pq2.y + pq2.z + pq2.w) + (pq3.x + pq3.y + pq3.z + pq3.w);
;         sRs[tid] = rsqrtf(sq * (1.0f / 1024.0f) + 1e-6f);
;       }
	s_lshl_b32 s11, s6, 8
	s_lshl_b32 s12, s4, 6
	s_add_u32 s11, s11, s12
	v_add_u32_e32 v238, s11, v248
	v_mul_lo_u32 v230, v238, s24
	s_lshl_b32 s11, s7, 7
	v_and_b32_e32 v239, 1, v249
	v_lshrrev_b32_e32 v240, 1, v249
	v_lshlrev_b32_e32 v239, 4, v239
	v_lshl_add_u32 v239, v240, 3, v239
	v_add_u32_e32 v239, s11, v239
	v_lshlrev_b32_e32 v239, 1, v239
	v_add_u32_e32 v230, v230, v239
	s_lshl_b32 s11, s24, 4
	v_add_u32_e32 v231, s11, v230
	v_add_u32_e32 v232, s11, v231
	v_add_u32_e32 v233, s11, v232
	s_nop 7
	v_add_u32_e32 v239, s33, v242
	ds_read_b32 v234, v239
	ds_read_b32 v235, v239 offset:64
	ds_read_b32 v236, v239 offset:128
	ds_read_b32 v237, v239 offset:192
	s_waitcnt lgkmcnt(0)
	v_mul_f32_e32 v0, v0, v234
	v_mul_f32_e32 v1, v1, v234
	v_mul_f32_e32 v2, v2, v234
	v_mul_f32_e32 v3, v3, v234
	v_mul_f32_e32 v4, v4, v234
	v_mul_f32_e32 v5, v5, v234
	v_mul_f32_e32 v6, v6, v234
	v_mul_f32_e32 v7, v7, v234
	v_mul_f32_e32 v8, v8, v234
	v_mul_f32_e32 v9, v9, v234
	v_mul_f32_e32 v10, v10, v234
	v_mul_f32_e32 v11, v11, v234
	v_mul_f32_e32 v12, v12, v234
	v_mul_f32_e32 v13, v13, v234
	v_mul_f32_e32 v14, v14, v234
	v_mul_f32_e32 v15, v15, v234
	v_mul_f32_e32 v16, v16, v234
	v_mul_f32_e32 v17, v17, v234
	v_mul_f32_e32 v18, v18, v234
	v_mul_f32_e32 v19, v19, v234
	v_mul_f32_e32 v20, v20, v234
	v_mul_f32_e32 v21, v21, v234
	v_mul_f32_e32 v22, v22, v234
	v_mul_f32_e32 v23, v23, v234
	v_mul_f32_e32 v24, v24, v234
	v_mul_f32_e32 v25, v25, v234
	v_mul_f32_e32 v26, v26, v234
	v_mul_f32_e32 v27, v27, v234
	v_mul_f32_e32 v28, v28, v234
	v_mul_f32_e32 v29, v29, v234
	v_mul_f32_e32 v30, v30, v234
	v_mul_f32_e32 v31, v31, v234
	v_mul_f32_e32 v32, v32, v235
	v_mul_f32_e32 v33, v33, v235
	v_mul_f32_e32 v34, v34, v235
	v_mul_f32_e32 v35, v35, v235
	v_mul_f32_e32 v36, v36, v235
	v_mul_f32_e32 v37, v37, v235
	v_mul_f32_e32 v38, v38, v235
	v_mul_f32_e32 v39, v39, v235
	v_mul_f32_e32 v40, v40, v235
	v_mul_f32_e32 v41, v41, v235
	v_mul_f32_e32 v42, v42, v235
	v_mul_f32_e32 v43, v43, v235
	v_mul_f32_e32 v44, v44, v235
	v_mul_f32_e32 v45, v45, v235
	v_mul_f32_e32 v46, v46, v235
	v_mul_f32_e32 v47, v47, v235
	v_mul_f32_e32 v48, v48, v235
	v_mul_f32_e32 v49, v49, v235
	v_mul_f32_e32 v50, v50, v235
	v_mul_f32_e32 v51, v51, v235
	v_mul_f32_e32 v52, v52, v235
	v_mul_f32_e32 v53, v53, v235
	v_mul_f32_e32 v54, v54, v235
	v_mul_f32_e32 v55, v55, v235
	v_mul_f32_e32 v56, v56, v235
	v_mul_f32_e32 v57, v57, v235
	v_mul_f32_e32 v58, v58, v235
	v_mul_f32_e32 v59, v59, v235
	v_mul_f32_e32 v60, v60, v235
	v_mul_f32_e32 v61, v61, v235
	v_mul_f32_e32 v62, v62, v235
	v_mul_f32_e32 v63, v63, v235
	v_mul_f32_e32 v64, v64, v236
	v_mul_f32_e32 v65, v65, v236
	v_mul_f32_e32 v66, v66, v236
	v_mul_f32_e32 v67, v67, v236
	v_mul_f32_e32 v68, v68, v236
	v_mul_f32_e32 v69, v69, v236
	v_mul_f32_e32 v70, v70, v236
	v_mul_f32_e32 v71, v71, v236
	v_mul_f32_e32 v72, v72, v236
	v_mul_f32_e32 v73, v73, v236
	v_mul_f32_e32 v74, v74, v236
	v_mul_f32_e32 v75, v75, v236
	v_mul_f32_e32 v76, v76, v236
	v_mul_f32_e32 v77, v77, v236
	v_mul_f32_e32 v78, v78, v236
	v_mul_f32_e32 v79, v79, v236
	v_mul_f32_e32 v80, v80, v236
	v_mul_f32_e32 v81, v81, v236
	v_mul_f32_e32 v82, v82, v236
	v_mul_f32_e32 v83, v83, v236
	v_mul_f32_e32 v84, v84, v236
	v_mul_f32_e32 v85, v85, v236
	v_mul_f32_e32 v86, v86, v236
	v_mul_f32_e32 v87, v87, v236
	v_mul_f32_e32 v88, v88, v236
	v_mul_f32_e32 v89, v89, v236
	v_mul_f32_e32 v90, v90, v236
	v_mul_f32_e32 v91, v91, v236
	v_mul_f32_e32 v92, v92, v236
	v_mul_f32_e32 v93, v93, v236
	v_mul_f32_e32 v94, v94, v236
	v_mul_f32_e32 v95, v95, v236
	v_mul_f32_e32 v96, v96, v237
	v_mul_f32_e32 v97, v97, v237
	v_mul_f32_e32 v98, v98, v237
	v_mul_f32_e32 v99, v99, v237
	v_mul_f32_e32 v100, v100, v237
	v_mul_f32_e32 v101, v101, v237
	v_mul_f32_e32 v102, v102, v237
	v_mul_f32_e32 v103, v103, v237
	v_mul_f32_e32 v104, v104, v237
	v_mul_f32_e32 v105, v105, v237
	v_mul_f32_e32 v106, v106, v237
	v_mul_f32_e32 v107, v107, v237
	v_mul_f32_e32 v108, v108, v237
	v_mul_f32_e32 v109, v109, v237
	v_mul_f32_e32 v110, v110, v237
	v_mul_f32_e32 v111, v111, v237
	v_mul_f32_e32 v112, v112, v237
	v_mul_f32_e32 v113, v113, v237
	v_mul_f32_e32 v114, v114, v237
	v_mul_f32_e32 v115, v115, v237
	v_mul_f32_e32 v116, v116, v237
	v_mul_f32_e32 v117, v117, v237
	v_mul_f32_e32 v118, v118, v237
	v_mul_f32_e32 v119, v119, v237
	v_mul_f32_e32 v120, v120, v237
	v_mul_f32_e32 v121, v121, v237
	v_mul_f32_e32 v122, v122, v237
	v_mul_f32_e32 v123, v123, v237
	v_mul_f32_e32 v124, v124, v237
	v_mul_f32_e32 v125, v125, v237
	v_mul_f32_e32 v126, v126, v237
	v_mul_f32_e32 v127, v127, v237
	s_cmp_eq_u32 s30, 0
	s_cbranch_scc1 .Lgm_norelu
; template <int EPI> ...
;     ...
;     if (EPI == EPI_SCALE || EPI == EPI_PLAIN || EPI == EPI_FF1) {
; #pragma unroll
;       for (int i = 0; i < 16; i++) {
;         const int rl = rbase + (i & 3) + 8 * (i >> 2);
;         const int row = m0 + rl;
;         float v0 = acc0[i], v1 = acc1[i];
;         if (EPI != EPI_PLAIN) { float rs = sRs[rl]; v0 *= rs; v1 *= rs; }
;         if (EPI == EPI_FF1) { v0 = fmaxf(v0, 0.f); v1 = fmaxf(v1, 0.f); v0 *= v0; v1 *= v1; }
;         outb[(size_t)row * ldo + c0] = f2bf(v0);
;         outb[(size_t)row * ldo + c1] = f2bf(v1);
;       }
	v_max_f32_e32 v0, 0, v0
	v_mul_f32_e32 v0, v0, v0
	v_max_f32_e32 v1, 0, v1
	v_mul_f32_e32 v1, v1, v1
	v_max_f32_e32 v2, 0, v2
	v_mul_f32_e32 v2, v2, v2
	v_max_f32_e32 v3, 0, v3
	v_mul_f32_e32 v3, v3, v3
	v_max_f32_e32 v4, 0, v4
	v_mul_f32_e32 v4, v4, v4
	v_max_f32_e32 v5, 0, v5
	v_mul_f32_e32 v5, v5, v5
	v_max_f32_e32 v6, 0, v6
	v_mul_f32_e32 v6, v6, v6
	v_max_f32_e32 v7, 0, v7
	v_mul_f32_e32 v7, v7, v7
	v_max_f32_e32 v8, 0, v8
	v_mul_f32_e32 v8, v8, v8
	v_max_f32_e32 v9, 0, v9
	v_mul_f32_e32 v9, v9, v9
	v_max_f32_e32 v10, 0, v10
	v_mul_f32_e32 v10, v10, v10
	v_max_f32_e32 v11, 0, v11
	v_mul_f32_e32 v11, v11, v11
	v_max_f32_e32 v12, 0, v12
	v_mul_f32_e32 v12, v12, v12
	v_max_f32_e32 v13, 0, v13
	v_mul_f32_e32 v13, v13, v13
	v_max_f32_e32 v14, 0, v14
	v_mul_f32_e32 v14, v14, v14
	v_max_f32_e32 v15, 0, v15
	v_mul_f32_e32 v15, v15, v15
	v_max_f32_e32 v16, 0, v16
	v_mul_f32_e32 v16, v16, v16
	v_max_f32_e32 v17, 0, v17
	v_mul_f32_e32 v17, v17, v17
	v_max_f32_e32 v18, 0, v18
	v_mul_f32_e32 v18, v18, v18
	v_max_f32_e32 v19, 0, v19
	v_mul_f32_e32 v19, v19, v19
	v_max_f32_e32 v20, 0, v20
	v_mul_f32_e32 v20, v20, v20
	v_max_f32_e32 v21, 0, v21
	v_mul_f32_e32 v21, v21, v21
	v_max_f32_e32 v22, 0, v22
	v_mul_f32_e32 v22, v22, v22
	v_max_f32_e32 v23, 0, v23
	v_mul_f32_e32 v23, v23, v23
	v_max_f32_e32 v24, 0, v24
	v_mul_f32_e32 v24, v24, v24
	v_max_f32_e32 v25, 0, v25
	v_mul_f32_e32 v25, v25, v25
	v_max_f32_e32 v26, 0, v26
	v_mul_f32_e32 v26, v26, v26
	v_max_f32_e32 v27, 0, v27
	v_mul_f32_e32 v27, v27, v27
	v_max_f32_e32 v28, 0, v28
	v_mul_f32_e32 v28, v28, v28
	v_max_f32_e32 v29, 0, v29
	v_mul_f32_e32 v29, v29, v29
	v_max_f32_e32 v30, 0, v30
	v_mul_f32_e32 v30, v30, v30
	v_max_f32_e32 v31, 0, v31
	v_mul_f32_e32 v31, v31, v31
	v_max_f32_e32 v32, 0, v32
	v_mul_f32_e32 v32, v32, v32
	v_max_f32_e32 v33, 0, v33
	v_mul_f32_e32 v33, v33, v33
	v_max_f32_e32 v34, 0, v34
	v_mul_f32_e32 v34, v34, v34
	v_max_f32_e32 v35, 0, v35
	v_mul_f32_e32 v35, v35, v35
	v_max_f32_e32 v36, 0, v36
	v_mul_f32_e32 v36, v36, v36
	v_max_f32_e32 v37, 0, v37
	v_mul_f32_e32 v37, v37, v37
	v_max_f32_e32 v38, 0, v38
	v_mul_f32_e32 v38, v38, v38
	v_max_f32_e32 v39, 0, v39
	v_mul_f32_e32 v39, v39, v39
	v_max_f32_e32 v40, 0, v40
	v_mul_f32_e32 v40, v40, v40
	v_max_f32_e32 v41, 0, v41
	v_mul_f32_e32 v41, v41, v41
	v_max_f32_e32 v42, 0, v42
	v_mul_f32_e32 v42, v42, v42
	v_max_f32_e32 v43, 0, v43
	v_mul_f32_e32 v43, v43, v43
	v_max_f32_e32 v44, 0, v44
	v_mul_f32_e32 v44, v44, v44
	v_max_f32_e32 v45, 0, v45
	v_mul_f32_e32 v45, v45, v45
	v_max_f32_e32 v46, 0, v46
	v_mul_f32_e32 v46, v46, v46
	v_max_f32_e32 v47, 0, v47
	v_mul_f32_e32 v47, v47, v47
	v_max_f32_e32 v48, 0, v48
	v_mul_f32_e32 v48, v48, v48
	v_max_f32_e32 v49, 0, v49
	v_mul_f32_e32 v49, v49, v49
	v_max_f32_e32 v50, 0, v50
	v_mul_f32_e32 v50, v50, v50
	v_max_f32_e32 v51, 0, v51
	v_mul_f32_e32 v51, v51, v51
	v_max_f32_e32 v52, 0, v52
	v_mul_f32_e32 v52, v52, v52
	v_max_f32_e32 v53, 0, v53
	v_mul_f32_e32 v53, v53, v53
	v_max_f32_e32 v54, 0, v54
	v_mul_f32_e32 v54, v54, v54
	v_max_f32_e32 v55, 0, v55
	v_mul_f32_e32 v55, v55, v55
	v_max_f32_e32 v56, 0, v56
	v_mul_f32_e32 v56, v56, v56
	v_max_f32_e32 v57, 0, v57
	v_mul_f32_e32 v57, v57, v57
	v_max_f32_e32 v58, 0, v58
	v_mul_f32_e32 v58, v58, v58
	v_max_f32_e32 v59, 0, v59
	v_mul_f32_e32 v59, v59, v59
	v_max_f32_e32 v60, 0, v60
	v_mul_f32_e32 v60, v60, v60
	v_max_f32_e32 v61, 0, v61
	v_mul_f32_e32 v61, v61, v61
	v_max_f32_e32 v62, 0, v62
	v_mul_f32_e32 v62, v62, v62
	v_max_f32_e32 v63, 0, v63
	v_mul_f32_e32 v63, v63, v63
	v_max_f32_e32 v64, 0, v64
	v_mul_f32_e32 v64, v64, v64
	v_max_f32_e32 v65, 0, v65
	v_mul_f32_e32 v65, v65, v65
	v_max_f32_e32 v66, 0, v66
	v_mul_f32_e32 v66, v66, v66
	v_max_f32_e32 v67, 0, v67
	v_mul_f32_e32 v67, v67, v67
	v_max_f32_e32 v68, 0, v68
	v_mul_f32_e32 v68, v68, v68
	v_max_f32_e32 v69, 0, v69
	v_mul_f32_e32 v69, v69, v69
	v_max_f32_e32 v70, 0, v70
	v_mul_f32_e32 v70, v70, v70
	v_max_f32_e32 v71, 0, v71
	v_mul_f32_e32 v71, v71, v71
	v_max_f32_e32 v72, 0, v72
	v_mul_f32_e32 v72, v72, v72
	v_max_f32_e32 v73, 0, v73
	v_mul_f32_e32 v73, v73, v73
	v_max_f32_e32 v74, 0, v74
	v_mul_f32_e32 v74, v74, v74
	v_max_f32_e32 v75, 0, v75
	v_mul_f32_e32 v75, v75, v75
	v_max_f32_e32 v76, 0, v76
	v_mul_f32_e32 v76, v76, v76
	v_max_f32_e32 v77, 0, v77
	v_mul_f32_e32 v77, v77, v77
	v_max_f32_e32 v78, 0, v78
	v_mul_f32_e32 v78, v78, v78
	v_max_f32_e32 v79, 0, v79
	v_mul_f32_e32 v79, v79, v79
	v_max_f32_e32 v80, 0, v80
	v_mul_f32_e32 v80, v80, v80
	v_max_f32_e32 v81, 0, v81
	v_mul_f32_e32 v81, v81, v81
	v_max_f32_e32 v82, 0, v82
	v_mul_f32_e32 v82, v82, v82
	v_max_f32_e32 v83, 0, v83
	v_mul_f32_e32 v83, v83, v83
	v_max_f32_e32 v84, 0, v84
	v_mul_f32_e32 v84, v84, v84
	v_max_f32_e32 v85, 0, v85
	v_mul_f32_e32 v85, v85, v85
	v_max_f32_e32 v86, 0, v86
	v_mul_f32_e32 v86, v86, v86
	v_max_f32_e32 v87, 0, v87
	v_mul_f32_e32 v87, v87, v87
	v_max_f32_e32 v88, 0, v88
	v_mul_f32_e32 v88, v88, v88
	v_max_f32_e32 v89, 0, v89
	v_mul_f32_e32 v89, v89, v89
	v_max_f32_e32 v90, 0, v90
	v_mul_f32_e32 v90, v90, v90
	v_max_f32_e32 v91, 0, v91
	v_mul_f32_e32 v91, v91, v91
	v_max_f32_e32 v92, 0, v92
	v_mul_f32_e32 v92, v92, v92
	v_max_f32_e32 v93, 0, v93
	v_mul_f32_e32 v93, v93, v93
	v_max_f32_e32 v94, 0, v94
	v_mul_f32_e32 v94, v94, v94
	v_max_f32_e32 v95, 0, v95
	v_mul_f32_e32 v95, v95, v95
	v_max_f32_e32 v96, 0, v96
	v_mul_f32_e32 v96, v96, v96
	v_max_f32_e32 v97, 0, v97
	v_mul_f32_e32 v97, v97, v97
	v_max_f32_e32 v98, 0, v98
	v_mul_f32_e32 v98, v98, v98
	v_max_f32_e32 v99, 0, v99
	v_mul_f32_e32 v99, v99, v99
	v_max_f32_e32 v100, 0, v100
	v_mul_f32_e32 v100, v100, v100
	v_max_f32_e32 v101, 0, v101
; template <int EPI> ...
;     ...
;     if (EPI == EPI_SCALE || EPI == EPI_PLAIN || EPI == EPI_FF1) {
; #pragma unroll
;       for (int i = 0; i < 16; i++) {
;         const int rl = rbase + (i & 3) + 8 * (i >> 2);
;         const int row = m0 + rl;
;         float v0 = acc0[i], v1 = acc1[i];
;         if (EPI != EPI_PLAIN) { float rs = sRs[rl]; v0 *= rs; v1 *= rs; }
;         if (EPI == EPI_FF1) { v0 = fmaxf(v0, 0.f); v1 = fmaxf(v1, 0.f); v0 *= v0; v1 *= v1; }
;         outb[(size_t)row * ldo + c0] = f2bf(v0);
;         outb[(size_t)row * ldo + c1] = f2bf(v1);
;       }
	v_mul_f32_e32 v101, v101, v101
	v_max_f32_e32 v102, 0, v102
	v_mul_f32_e32 v102, v102, v102
	v_max_f32_e32 v103, 0, v103
	v_mul_f32_e32 v103, v103, v103
	v_max_f32_e32 v104, 0, v104
	v_mul_f32_e32 v104, v104, v104
	v_max_f32_e32 v105, 0, v105
	v_mul_f32_e32 v105, v105, v105
	v_max_f32_e32 v106, 0, v106
	v_mul_f32_e32 v106, v106, v106
	v_max_f32_e32 v107, 0, v107
	v_mul_f32_e32 v107, v107, v107
	v_max_f32_e32 v108, 0, v108
	v_mul_f32_e32 v108, v108, v108
	v_max_f32_e32 v109, 0, v109
	v_mul_f32_e32 v109, v109, v109
	v_max_f32_e32 v110, 0, v110
	v_mul_f32_e32 v110, v110, v110
	v_max_f32_e32 v111, 0, v111
	v_mul_f32_e32 v111, v111, v111
	v_max_f32_e32 v112, 0, v112
	v_mul_f32_e32 v112, v112, v112
	v_max_f32_e32 v113, 0, v113
	v_mul_f32_e32 v113, v113, v113
	v_max_f32_e32 v114, 0, v114
	v_mul_f32_e32 v114, v114, v114
	v_max_f32_e32 v115, 0, v115
	v_mul_f32_e32 v115, v115, v115
	v_max_f32_e32 v116, 0, v116
	v_mul_f32_e32 v116, v116, v116
	v_max_f32_e32 v117, 0, v117
	v_mul_f32_e32 v117, v117, v117
	v_max_f32_e32 v118, 0, v118
	v_mul_f32_e32 v118, v118, v118
	v_max_f32_e32 v119, 0, v119
	v_mul_f32_e32 v119, v119, v119
	v_max_f32_e32 v120, 0, v120
	v_mul_f32_e32 v120, v120, v120
	v_max_f32_e32 v121, 0, v121
	v_mul_f32_e32 v121, v121, v121
	v_max_f32_e32 v122, 0, v122
	v_mul_f32_e32 v122, v122, v122
	v_max_f32_e32 v123, 0, v123
	v_mul_f32_e32 v123, v123, v123
	v_max_f32_e32 v124, 0, v124
	v_mul_f32_e32 v124, v124, v124
	v_max_f32_e32 v125, 0, v125
	v_mul_f32_e32 v125, v125, v125
	v_max_f32_e32 v126, 0, v126
	v_mul_f32_e32 v126, v126, v126
	v_max_f32_e32 v127, 0, v127
	v_mul_f32_e32 v127, v127, v127
.Lgm_norelu:
	v_cvt_pk_bf16_f32 v0, v0, v1
	v_cvt_pk_bf16_f32 v1, v2, v3
	v_cvt_pk_bf16_f32 v2, v4, v5
	v_cvt_pk_bf16_f32 v3, v6, v7
	s_nop 1
	v_permlane16_swap_b32_e32 v0, v2
	v_permlane16_swap_b32_e32 v1, v3
	global_store_dwordx4 v230, v[0:3], s[22:23]
	v_cvt_pk_bf16_f32 v8, v8, v9
	v_cvt_pk_bf16_f32 v9, v10, v11
	v_cvt_pk_bf16_f32 v10, v12, v13
	v_cvt_pk_bf16_f32 v11, v14, v15
	s_nop 1
	v_permlane16_swap_b32_e32 v8, v10
	v_permlane16_swap_b32_e32 v9, v11
	global_store_dwordx4 v230, v[8:11], s[22:23] offset:64
	v_cvt_pk_bf16_f32 v16, v16, v17
	v_cvt_pk_bf16_f32 v17, v18, v19
	v_cvt_pk_bf16_f32 v18, v20, v21
	v_cvt_pk_bf16_f32 v19, v22, v23
	s_nop 1
	v_permlane16_swap_b32_e32 v16, v18
	v_permlane16_swap_b32_e32 v17, v19
	global_store_dwordx4 v230, v[16:19], s[22:23] offset:128
	v_cvt_pk_bf16_f32 v24, v24, v25
	v_cvt_pk_bf16_f32 v25, v26, v27
	v_cvt_pk_bf16_f32 v26, v28, v29
	v_cvt_pk_bf16_f32 v27, v30, v31
	s_nop 1
	v_permlane16_swap_b32_e32 v24, v26
	v_permlane16_swap_b32_e32 v25, v27
	global_store_dwordx4 v230, v[24:27], s[22:23] offset:192
	v_cvt_pk_bf16_f32 v32, v32, v33
	v_cvt_pk_bf16_f32 v33, v34, v35
	v_cvt_pk_bf16_f32 v34, v36, v37
	v_cvt_pk_bf16_f32 v35, v38, v39
	s_nop 1
	v_permlane16_swap_b32_e32 v32, v34
	v_permlane16_swap_b32_e32 v33, v35
	global_store_dwordx4 v231, v[32:35], s[22:23]
	v_cvt_pk_bf16_f32 v40, v40, v41
	v_cvt_pk_bf16_f32 v41, v42, v43
	v_cvt_pk_bf16_f32 v42, v44, v45
	v_cvt_pk_bf16_f32 v43, v46, v47
	s_nop 1
	v_permlane16_swap_b32_e32 v40, v42
	v_permlane16_swap_b32_e32 v41, v43
	global_store_dwordx4 v231, v[40:43], s[22:23] offset:64
	v_cvt_pk_bf16_f32 v48, v48, v49
	v_cvt_pk_bf16_f32 v49, v50, v51
	v_cvt_pk_bf16_f32 v50, v52, v53
	v_cvt_pk_bf16_f32 v51, v54, v55
	s_nop 1
	v_permlane16_swap_b32_e32 v48, v50
	v_permlane16_swap_b32_e32 v49, v51
	global_store_dwordx4 v231, v[48:51], s[22:23] offset:128
	v_cvt_pk_bf16_f32 v56, v56, v57
	v_cvt_pk_bf16_f32 v57, v58, v59
	v_cvt_pk_bf16_f32 v58, v60, v61
	v_cvt_pk_bf16_f32 v59, v62, v63
	s_nop 1
	v_permlane16_swap_b32_e32 v56, v58
	v_permlane16_swap_b32_e32 v57, v59
	global_store_dwordx4 v231, v[56:59], s[22:23] offset:192
	v_cvt_pk_bf16_f32 v64, v64, v65
	v_cvt_pk_bf16_f32 v65, v66, v67
	v_cvt_pk_bf16_f32 v66, v68, v69
	v_cvt_pk_bf16_f32 v67, v70, v71
	s_nop 1
	v_permlane16_swap_b32_e32 v64, v66
	v_permlane16_swap_b32_e32 v65, v67
	global_store_dwordx4 v232, v[64:67], s[22:23]
	v_cvt_pk_bf16_f32 v72, v72, v73
	v_cvt_pk_bf16_f32 v73, v74, v75
	v_cvt_pk_bf16_f32 v74, v76, v77
	v_cvt_pk_bf16_f32 v75, v78, v79
	s_nop 1
	v_permlane16_swap_b32_e32 v72, v74
	v_permlane16_swap_b32_e32 v73, v75
	global_store_dwordx4 v232, v[72:75], s[22:23] offset:64
	v_cvt_pk_bf16_f32 v80, v80, v81
	v_cvt_pk_bf16_f32 v81, v82, v83
	v_cvt_pk_bf16_f32 v82, v84, v85
	v_cvt_pk_bf16_f32 v83, v86, v87
	s_nop 1
	v_permlane16_swap_b32_e32 v80, v82
	v_permlane16_swap_b32_e32 v81, v83
	global_store_dwordx4 v232, v[80:83], s[22:23] offset:128
	v_cvt_pk_bf16_f32 v88, v88, v89
	v_cvt_pk_bf16_f32 v89, v90, v91
	v_cvt_pk_bf16_f32 v90, v92, v93
	v_cvt_pk_bf16_f32 v91, v94, v95
	s_nop 1
	v_permlane16_swap_b32_e32 v88, v90
	v_permlane16_swap_b32_e32 v89, v91
	global_store_dwordx4 v232, v[88:91], s[22:23] offset:192
	v_cvt_pk_bf16_f32 v96, v96, v97
	v_cvt_pk_bf16_f32 v97, v98, v99
	v_cvt_pk_bf16_f32 v98, v100, v101
	v_cvt_pk_bf16_f32 v99, v102, v103
	s_nop 1
	v_permlane16_swap_b32_e32 v96, v98
	v_permlane16_swap_b32_e32 v97, v99
	global_store_dwordx4 v233, v[96:99], s[22:23]
	v_cvt_pk_bf16_f32 v104, v104, v105
	v_cvt_pk_bf16_f32 v105, v106, v107
	v_cvt_pk_bf16_f32 v106, v108, v109
	v_cvt_pk_bf16_f32 v107, v110, v111
	s_nop 1
	v_permlane16_swap_b32_e32 v104, v106
	v_permlane16_swap_b32_e32 v105, v107
	global_store_dwordx4 v233, v[104:107], s[22:23] offset:64
	v_cvt_pk_bf16_f32 v112, v112, v113
	v_cvt_pk_bf16_f32 v113, v114, v115
	v_cvt_pk_bf16_f32 v114, v116, v117
	v_cvt_pk_bf16_f32 v115, v118, v119
	s_nop 1
	v_permlane16_swap_b32_e32 v112, v114
	v_permlane16_swap_b32_e32 v113, v115
	global_store_dwordx4 v233, v[112:115], s[22:23] offset:128
	v_cvt_pk_bf16_f32 v120, v120, v121
	v_cvt_pk_bf16_f32 v121, v122, v123
	v_cvt_pk_bf16_f32 v122, v124, v125
	v_cvt_pk_bf16_f32 v123, v126, v127
	s_nop 1
	v_permlane16_swap_b32_e32 v120, v122
	v_permlane16_swap_b32_e32 v121, v123
	global_store_dwordx4 v233, v[120:123], s[22:23] offset:192
	s_xor_b32 s33, s33, 0x400
	s_branch .Lgc_next
; template <int EPI> ...
;     ...
;     } else if (EPI == EPI_RES) {
; #pragma unroll
;       for (int i = 0; i < 16; i++) {
;         const int rl = rbase + (i & 3) + 8 * (i >> 2);
;         const int row = m0 + rl;
;         float v0 = acc0[i], v1 = acc1[i];
;         xf[(size_t)row * 1024 + c0] = v0;
;         xf[(size_t)row * 1024 + c1] = v1;
;         outb[(size_t)row * 1024 + c0] = f2bf(v0);
;         outb[(size_t)row * 1024 + c1] = f2bf(v1);
;         float s = hsum32(v0 * v0 + v1 * v1);
;         if ((lane & 31) == 0) part[(size_t)row * 16 + nt * 2 + wn] = s;
;       }
; template <int EPI>
; __device__ __forceinline__ void gemm_phase(const Params& p, const u16* __restrict__ A, int lda, const u16* __restrict__ BT, int ldb,
;                            int K, int N, u16* __restrict__ outb, int ldo, int resid_in, int boff) {
;     ...
;     if (EPI == EPI_RES && !part_unit) {
;       const int cc0 = n0 + wn * 64 + (lane & 31);
;       float* xfq = p.out;
; #pragma unroll
;       for (int i = 0; i < 16; i++) {
;         const int row = m0 + wm * 64 + 4 * (lane >> 5) + (i & 3) + 8 * (i >> 2);
;         const float* ra = resid_in ? xrow(p, row) : (xfq + (size_t)row * 1024);
;         const float* rb = resid_in ? xrow(p, row + 32) : (xfq + (size_t)(row + 32) * 1024);
;         acc00[i] = ra[cc0]; acc01[i] = ra[cc0 + 32];
;         acc10[i] = rb[cc0]; acc11[i] = rb[cc0 + 32];
;       }
.Lgc_epi_res:
	s_lshl_b32 s11, s6, 8
	s_lshl_b32 s12, s4, 6
	s_add_u32 s11, s11, s12
	v_add_u32_e32 v238, s11, v248
	v_lshlrev_b32_e32 v243, 12, v238
	s_lshl_b32 s11, s7, 7
	v_lshl_add_u32 v239, v249, 2, s11
	v_lshlrev_b32_e32 v239, 2, v239
	v_add_u32_e32 v243, v243, v239
	v_add_u32_e32 v244, 0x10000, v243
	v_add_u32_e32 v245, 0x10000, v244
	v_add_u32_e32 v246, 0x10000, v245
	v_lshlrev_b32_e32 v247, 6, v238
	s_lshl_b32 s11, s7, 3
	v_add_u32_e32 v247, s11, v247
	s_lshl_b32 s11, s6, 8
	s_lshl_b32 s12, s4, 6
	s_add_u32 s11, s11, s12
	v_add_u32_e32 v238, s11, v248
	v_mul_lo_u32 v230, v238, s24
	s_lshl_b32 s11, s7, 7
	v_and_b32_e32 v239, 1, v249
	v_lshrrev_b32_e32 v240, 1, v249
	v_lshlrev_b32_e32 v239, 4, v239
	v_lshl_add_u32 v239, v240, 3, v239
	v_add_u32_e32 v239, s11, v239
	v_lshlrev_b32_e32 v239, 1, v239
	v_add_u32_e32 v230, v230, v239
	s_lshl_b32 s11, s24, 4
	v_add_u32_e32 v231, s11, v230
	v_add_u32_e32 v232, s11, v231
	v_add_u32_e32 v233, s11, v232
	global_load_dwordx4 v[130:133], v243, s[48:49]
	global_load_dwordx4 v[134:137], v243, s[48:49] offset:64
	global_load_dwordx4 v[138:141], v243, s[48:49] offset:128
	global_load_dwordx4 v[142:145], v243, s[48:49] offset:192
	global_load_dwordx4 v[146:149], v243, s[48:49] offset:256
	global_load_dwordx4 v[150:153], v243, s[48:49] offset:320
	global_load_dwordx4 v[154:157], v243, s[48:49] offset:384
	global_load_dwordx4 v[158:161], v243, s[48:49] offset:448
	global_load_dwordx4 v[162:165], v244, s[48:49]
	global_load_dwordx4 v[166:169], v244, s[48:49] offset:64
	global_load_dwordx4 v[170:173], v244, s[48:49] offset:128
	global_load_dwordx4 v[174:177], v244, s[48:49] offset:192
	global_load_dwordx4 v[178:181], v244, s[48:49] offset:256
	global_load_dwordx4 v[182:185], v244, s[48:49] offset:320
	global_load_dwordx4 v[186:189], v244, s[48:49] offset:384
	global_load_dwordx4 v[190:193], v244, s[48:49] offset:448
	global_load_dwordx4 v[194:197], v245, s[48:49]
	global_load_dwordx4 v[198:201], v245, s[48:49] offset:64
	global_load_dwordx4 v[202:205], v245, s[48:49] offset:128
	global_load_dwordx4 v[206:209], v245, s[48:49] offset:192
	global_load_dwordx4 v[210:213], v245, s[48:49] offset:256
	global_load_dwordx4 v[214:217], v245, s[48:49] offset:320
	global_load_dwordx4 v[218:221], v245, s[48:49] offset:384
	global_load_dwordx4 v[222:225], v245, s[48:49] offset:448
	s_waitcnt vmcnt(23)
	v_add_f32_e32 v0, v0, v130
	v_add_f32_e32 v1, v1, v131
	v_add_f32_e32 v2, v2, v132
	v_add_f32_e32 v3, v3, v133
	global_load_dwordx4 v[130:133], v246, s[48:49]
	s_waitcnt vmcnt(23)
	v_add_f32_e32 v4, v4, v134
	v_add_f32_e32 v5, v5, v135
	v_add_f32_e32 v6, v6, v136
	v_add_f32_e32 v7, v7, v137
	global_load_dwordx4 v[134:137], v246, s[48:49] offset:64
	s_waitcnt vmcnt(23)
	v_add_f32_e32 v8, v8, v138
	v_add_f32_e32 v9, v9, v139
	v_add_f32_e32 v10, v10, v140
	v_add_f32_e32 v11, v11, v141
	global_load_dwordx4 v[138:141], v246, s[48:49] offset:128
	s_waitcnt vmcnt(23)
	v_add_f32_e32 v12, v12, v142
	v_add_f32_e32 v13, v13, v143
	v_add_f32_e32 v14, v14, v144
	v_add_f32_e32 v15, v15, v145
	global_load_dwordx4 v[142:145], v246, s[48:49] offset:192
	s_waitcnt vmcnt(23)
	v_add_f32_e32 v16, v16, v146
	v_add_f32_e32 v17, v17, v147
	v_add_f32_e32 v18, v18, v148
	v_add_f32_e32 v19, v19, v149
	global_load_dwordx4 v[146:149], v246, s[48:49] offset:256
	s_waitcnt vmcnt(23)
	v_add_f32_e32 v20, v20, v150
	v_add_f32_e32 v21, v21, v151
	v_add_f32_e32 v22, v22, v152
	v_add_f32_e32 v23, v23, v153
	global_load_dwordx4 v[150:153], v246, s[48:49] offset:320
	s_waitcnt vmcnt(23)
	v_add_f32_e32 v24, v24, v154
	v_add_f32_e32 v25, v25, v155
	v_add_f32_e32 v26, v26, v156
	v_add_f32_e32 v27, v27, v157
	global_load_dwordx4 v[154:157], v246, s[48:49] offset:384
	s_waitcnt vmcnt(23)
	v_add_f32_e32 v28, v28, v158
	v_add_f32_e32 v29, v29, v159
	v_add_f32_e32 v30, v30, v160
	v_add_f32_e32 v31, v31, v161
	global_load_dwordx4 v[158:161], v246, s[48:49] offset:448
	s_waitcnt vmcnt(23)
	v_add_f32_e32 v32, v32, v162
	v_add_f32_e32 v33, v33, v163
	v_add_f32_e32 v34, v34, v164
	v_add_f32_e32 v35, v35, v165
	s_waitcnt vmcnt(22)
	v_add_f32_e32 v36, v36, v166
	v_add_f32_e32 v37, v37, v167
	v_add_f32_e32 v38, v38, v168
	v_add_f32_e32 v39, v39, v169
	s_waitcnt vmcnt(21)
	v_add_f32_e32 v40, v40, v170
	v_add_f32_e32 v41, v41, v171
	v_add_f32_e32 v42, v42, v172
	v_add_f32_e32 v43, v43, v173
	s_waitcnt vmcnt(20)
	v_add_f32_e32 v44, v44, v174
	v_add_f32_e32 v45, v45, v175
	v_add_f32_e32 v46, v46, v176
	v_add_f32_e32 v47, v47, v177
	s_waitcnt vmcnt(19)
	v_add_f32_e32 v48, v48, v178
	v_add_f32_e32 v49, v49, v179
	v_add_f32_e32 v50, v50, v180
	v_add_f32_e32 v51, v51, v181
	s_waitcnt vmcnt(18)
	v_add_f32_e32 v52, v52, v182
	v_add_f32_e32 v53, v53, v183
	v_add_f32_e32 v54, v54, v184
	v_add_f32_e32 v55, v55, v185
	s_waitcnt vmcnt(17)
	v_add_f32_e32 v56, v56, v186
	v_add_f32_e32 v57, v57, v187
	v_add_f32_e32 v58, v58, v188
	v_add_f32_e32 v59, v59, v189
	s_waitcnt vmcnt(16)
	v_add_f32_e32 v60, v60, v190
	v_add_f32_e32 v61, v61, v191
	v_add_f32_e32 v62, v62, v192
	v_add_f32_e32 v63, v63, v193
	s_waitcnt vmcnt(15)
	v_add_f32_e32 v64, v64, v194
	v_add_f32_e32 v65, v65, v195
	v_add_f32_e32 v66, v66, v196
	v_add_f32_e32 v67, v67, v197
	s_waitcnt vmcnt(14)
	v_add_f32_e32 v68, v68, v198
	v_add_f32_e32 v69, v69, v199
	v_add_f32_e32 v70, v70, v200
	v_add_f32_e32 v71, v71, v201
	s_waitcnt vmcnt(13)
	v_add_f32_e32 v72, v72, v202
	v_add_f32_e32 v73, v73, v203
	v_add_f32_e32 v74, v74, v204
	v_add_f32_e32 v75, v75, v205
	s_waitcnt vmcnt(12)
	v_add_f32_e32 v76, v76, v206
	v_add_f32_e32 v77, v77, v207
	v_add_f32_e32 v78, v78, v208
	v_add_f32_e32 v79, v79, v209
	s_waitcnt vmcnt(11)
; template <int EPI> ...
;     ...
;     } else if (EPI == EPI_RES) {
; #pragma unroll
;       for (int i = 0; i < 16; i++) {
;         const int rl = rbase + (i & 3) + 8 * (i >> 2);
;         const int row = m0 + rl;
;         float v0 = acc0[i], v1 = acc1[i];
;         xf[(size_t)row * 1024 + c0] = v0;
;         xf[(size_t)row * 1024 + c1] = v1;
;         outb[(size_t)row * 1024 + c0] = f2bf(v0);
;         outb[(size_t)row * 1024 + c1] = f2bf(v1);
;         float s = hsum32(v0 * v0 + v1 * v1);
;         if ((lane & 31) == 0) part[(size_t)row * 16 + nt * 2 + wn] = s;
;       }
	v_add_f32_e32 v80, v80, v210
	v_add_f32_e32 v81, v81, v211
	v_add_f32_e32 v82, v82, v212
	v_add_f32_e32 v83, v83, v213
	s_waitcnt vmcnt(10)
	v_add_f32_e32 v84, v84, v214
	v_add_f32_e32 v85, v85, v215
	v_add_f32_e32 v86, v86, v216
	v_add_f32_e32 v87, v87, v217
	s_waitcnt vmcnt(9)
	v_add_f32_e32 v88, v88, v218
	v_add_f32_e32 v89, v89, v219
	v_add_f32_e32 v90, v90, v220
	v_add_f32_e32 v91, v91, v221
	s_waitcnt vmcnt(8)
	v_add_f32_e32 v92, v92, v222
	v_add_f32_e32 v93, v93, v223
	v_add_f32_e32 v94, v94, v224
	v_add_f32_e32 v95, v95, v225
	s_waitcnt vmcnt(7)
	v_add_f32_e32 v96, v96, v130
	v_add_f32_e32 v97, v97, v131
	v_add_f32_e32 v98, v98, v132
	v_add_f32_e32 v99, v99, v133
	s_waitcnt vmcnt(6)
	v_add_f32_e32 v100, v100, v134
	v_add_f32_e32 v101, v101, v135
	v_add_f32_e32 v102, v102, v136
	v_add_f32_e32 v103, v103, v137
	s_waitcnt vmcnt(5)
	v_add_f32_e32 v104, v104, v138
	v_add_f32_e32 v105, v105, v139
	v_add_f32_e32 v106, v106, v140
	v_add_f32_e32 v107, v107, v141
	s_waitcnt vmcnt(4)
	v_add_f32_e32 v108, v108, v142
	v_add_f32_e32 v109, v109, v143
	v_add_f32_e32 v110, v110, v144
	v_add_f32_e32 v111, v111, v145
	s_waitcnt vmcnt(3)
	v_add_f32_e32 v112, v112, v146
	v_add_f32_e32 v113, v113, v147
	v_add_f32_e32 v114, v114, v148
	v_add_f32_e32 v115, v115, v149
	s_waitcnt vmcnt(2)
	v_add_f32_e32 v116, v116, v150
	v_add_f32_e32 v117, v117, v151
	v_add_f32_e32 v118, v118, v152
	v_add_f32_e32 v119, v119, v153
	s_waitcnt vmcnt(1)
	v_add_f32_e32 v120, v120, v154
	v_add_f32_e32 v121, v121, v155
	v_add_f32_e32 v122, v122, v156
	v_add_f32_e32 v123, v123, v157
	s_waitcnt vmcnt(0)
	v_add_f32_e32 v124, v124, v158
	v_add_f32_e32 v125, v125, v159
	v_add_f32_e32 v126, v126, v160
	v_add_f32_e32 v127, v127, v161
	global_store_dwordx4 v243, v[0:3], s[94:95]
	v_mul_f32_e32 v234, v0, v0
	v_fmac_f32_e32 v234, v1, v1
	v_fmac_f32_e32 v234, v2, v2
	v_fmac_f32_e32 v234, v3, v3
	global_store_dwordx4 v243, v[4:7], s[94:95] offset:64
	v_fmac_f32_e32 v234, v4, v4
	v_fmac_f32_e32 v234, v5, v5
	v_fmac_f32_e32 v234, v6, v6
	v_fmac_f32_e32 v234, v7, v7
	global_store_dwordx4 v243, v[8:11], s[94:95] offset:128
	v_fmac_f32_e32 v234, v8, v8
	v_fmac_f32_e32 v234, v9, v9
	v_fmac_f32_e32 v234, v10, v10
	v_fmac_f32_e32 v234, v11, v11
	global_store_dwordx4 v243, v[12:15], s[94:95] offset:192
	v_fmac_f32_e32 v234, v12, v12
	v_fmac_f32_e32 v234, v13, v13
	v_fmac_f32_e32 v234, v14, v14
	v_fmac_f32_e32 v234, v15, v15
	global_store_dwordx4 v243, v[16:19], s[94:95] offset:256
	v_fmac_f32_e32 v234, v16, v16
	v_fmac_f32_e32 v234, v17, v17
	v_fmac_f32_e32 v234, v18, v18
	v_fmac_f32_e32 v234, v19, v19
	global_store_dwordx4 v243, v[20:23], s[94:95] offset:320
	v_fmac_f32_e32 v234, v20, v20
	v_fmac_f32_e32 v234, v21, v21
	v_fmac_f32_e32 v234, v22, v22
	v_fmac_f32_e32 v234, v23, v23
	global_store_dwordx4 v243, v[24:27], s[94:95] offset:384
	v_fmac_f32_e32 v234, v24, v24
	v_fmac_f32_e32 v234, v25, v25
	v_fmac_f32_e32 v234, v26, v26
	v_fmac_f32_e32 v234, v27, v27
	global_store_dwordx4 v243, v[28:31], s[94:95] offset:448
	v_fmac_f32_e32 v234, v28, v28
	v_fmac_f32_e32 v234, v29, v29
	v_fmac_f32_e32 v234, v30, v30
	v_fmac_f32_e32 v234, v31, v31
	global_store_dwordx4 v244, v[32:35], s[94:95]
	v_mul_f32_e32 v235, v32, v32
	v_fmac_f32_e32 v235, v33, v33
	v_fmac_f32_e32 v235, v34, v34
	v_fmac_f32_e32 v235, v35, v35
	global_store_dwordx4 v244, v[36:39], s[94:95] offset:64
	v_fmac_f32_e32 v235, v36, v36
	v_fmac_f32_e32 v235, v37, v37
	v_fmac_f32_e32 v235, v38, v38
	v_fmac_f32_e32 v235, v39, v39
	global_store_dwordx4 v244, v[40:43], s[94:95] offset:128
	v_fmac_f32_e32 v235, v40, v40
	v_fmac_f32_e32 v235, v41, v41
	v_fmac_f32_e32 v235, v42, v42
	v_fmac_f32_e32 v235, v43, v43
	global_store_dwordx4 v244, v[44:47], s[94:95] offset:192
	v_fmac_f32_e32 v235, v44, v44
	v_fmac_f32_e32 v235, v45, v45
	v_fmac_f32_e32 v235, v46, v46
	v_fmac_f32_e32 v235, v47, v47
	global_store_dwordx4 v244, v[48:51], s[94:95] offset:256
	v_fmac_f32_e32 v235, v48, v48
	v_fmac_f32_e32 v235, v49, v49
	v_fmac_f32_e32 v235, v50, v50
	v_fmac_f32_e32 v235, v51, v51
	global_store_dwordx4 v244, v[52:55], s[94:95] offset:320
	v_fmac_f32_e32 v235, v52, v52
	v_fmac_f32_e32 v235, v53, v53
	v_fmac_f32_e32 v235, v54, v54
	v_fmac_f32_e32 v235, v55, v55
	global_store_dwordx4 v244, v[56:59], s[94:95] offset:384
	v_fmac_f32_e32 v235, v56, v56
	v_fmac_f32_e32 v235, v57, v57
	v_fmac_f32_e32 v235, v58, v58
	v_fmac_f32_e32 v235, v59, v59
	global_store_dwordx4 v244, v[60:63], s[94:95] offset:448
	v_fmac_f32_e32 v235, v60, v60
	v_fmac_f32_e32 v235, v61, v61
	v_fmac_f32_e32 v235, v62, v62
	v_fmac_f32_e32 v235, v63, v63
	global_store_dwordx4 v245, v[64:67], s[94:95]
	v_mul_f32_e32 v236, v64, v64
	v_fmac_f32_e32 v236, v65, v65
	v_fmac_f32_e32 v236, v66, v66
	v_fmac_f32_e32 v236, v67, v67
	global_store_dwordx4 v245, v[68:71], s[94:95] offset:64
	v_fmac_f32_e32 v236, v68, v68
	v_fmac_f32_e32 v236, v69, v69
	v_fmac_f32_e32 v236, v70, v70
	v_fmac_f32_e32 v236, v71, v71
	global_store_dwordx4 v245, v[72:75], s[94:95] offset:128
	v_fmac_f32_e32 v236, v72, v72
	v_fmac_f32_e32 v236, v73, v73
	v_fmac_f32_e32 v236, v74, v74
	v_fmac_f32_e32 v236, v75, v75
	global_store_dwordx4 v245, v[76:79], s[94:95] offset:192
	v_fmac_f32_e32 v236, v76, v76
	v_fmac_f32_e32 v236, v77, v77
	v_fmac_f32_e32 v236, v78, v78
	v_fmac_f32_e32 v236, v79, v79
	global_store_dwordx4 v245, v[80:83], s[94:95] offset:256
	v_fmac_f32_e32 v236, v80, v80
	v_fmac_f32_e32 v236, v81, v81
	v_fmac_f32_e32 v236, v82, v82
	v_fmac_f32_e32 v236, v83, v83
	global_store_dwordx4 v245, v[84:87], s[94:95] offset:320
	v_fmac_f32_e32 v236, v84, v84
	v_fmac_f32_e32 v236, v85, v85
	v_fmac_f32_e32 v236, v86, v86
; template <int EPI> ...
;     ...
;     } else if (EPI == EPI_RES) {
; #pragma unroll
;       for (int i = 0; i < 16; i++) {
;         const int rl = rbase + (i & 3) + 8 * (i >> 2);
;         const int row = m0 + rl;
;         float v0 = acc0[i], v1 = acc1[i];
;         xf[(size_t)row * 1024 + c0] = v0;
;         xf[(size_t)row * 1024 + c1] = v1;
;         outb[(size_t)row * 1024 + c0] = f2bf(v0);
;         outb[(size_t)row * 1024 + c1] = f2bf(v1);
;         float s = hsum32(v0 * v0 + v1 * v1);
;         if ((lane & 31) == 0) part[(size_t)row * 16 + nt * 2 + wn] = s;
;       }
	v_fmac_f32_e32 v236, v87, v87
	global_store_dwordx4 v245, v[88:91], s[94:95] offset:384
	v_fmac_f32_e32 v236, v88, v88
	v_fmac_f32_e32 v236, v89, v89
	v_fmac_f32_e32 v236, v90, v90
	v_fmac_f32_e32 v236, v91, v91
	global_store_dwordx4 v245, v[92:95], s[94:95] offset:448
	v_fmac_f32_e32 v236, v92, v92
	v_fmac_f32_e32 v236, v93, v93
	v_fmac_f32_e32 v236, v94, v94
	v_fmac_f32_e32 v236, v95, v95
	global_store_dwordx4 v246, v[96:99], s[94:95]
	v_mul_f32_e32 v237, v96, v96
	v_fmac_f32_e32 v237, v97, v97
	v_fmac_f32_e32 v237, v98, v98
	v_fmac_f32_e32 v237, v99, v99
	global_store_dwordx4 v246, v[100:103], s[94:95] offset:64
	v_fmac_f32_e32 v237, v100, v100
	v_fmac_f32_e32 v237, v101, v101
	v_fmac_f32_e32 v237, v102, v102
	v_fmac_f32_e32 v237, v103, v103
	global_store_dwordx4 v246, v[104:107], s[94:95] offset:128
	v_fmac_f32_e32 v237, v104, v104
	v_fmac_f32_e32 v237, v105, v105
	v_fmac_f32_e32 v237, v106, v106
	v_fmac_f32_e32 v237, v107, v107
	global_store_dwordx4 v246, v[108:111], s[94:95] offset:192
	v_fmac_f32_e32 v237, v108, v108
	v_fmac_f32_e32 v237, v109, v109
	v_fmac_f32_e32 v237, v110, v110
	v_fmac_f32_e32 v237, v111, v111
	global_store_dwordx4 v246, v[112:115], s[94:95] offset:256
	v_fmac_f32_e32 v237, v112, v112
	v_fmac_f32_e32 v237, v113, v113
	v_fmac_f32_e32 v237, v114, v114
	v_fmac_f32_e32 v237, v115, v115
	global_store_dwordx4 v246, v[116:119], s[94:95] offset:320
	v_fmac_f32_e32 v237, v116, v116
	v_fmac_f32_e32 v237, v117, v117
	v_fmac_f32_e32 v237, v118, v118
	v_fmac_f32_e32 v237, v119, v119
	global_store_dwordx4 v246, v[120:123], s[94:95] offset:384
	v_fmac_f32_e32 v237, v120, v120
	v_fmac_f32_e32 v237, v121, v121
	v_fmac_f32_e32 v237, v122, v122
	v_fmac_f32_e32 v237, v123, v123
	global_store_dwordx4 v246, v[124:127], s[94:95] offset:448
	v_fmac_f32_e32 v237, v124, v124
	v_fmac_f32_e32 v237, v125, v125
	v_fmac_f32_e32 v237, v126, v126
	v_fmac_f32_e32 v237, v127, v127
	v_cvt_pk_bf16_f32 v0, v0, v1
	v_cvt_pk_bf16_f32 v1, v2, v3
	v_cvt_pk_bf16_f32 v2, v4, v5
	v_cvt_pk_bf16_f32 v3, v6, v7
	s_nop 1
	v_permlane16_swap_b32_e32 v0, v2
	v_permlane16_swap_b32_e32 v1, v3
	global_store_dwordx4 v230, v[0:3], s[22:23]
	v_cvt_pk_bf16_f32 v8, v8, v9
	v_cvt_pk_bf16_f32 v9, v10, v11
	v_cvt_pk_bf16_f32 v10, v12, v13
	v_cvt_pk_bf16_f32 v11, v14, v15
	s_nop 1
	v_permlane16_swap_b32_e32 v8, v10
	v_permlane16_swap_b32_e32 v9, v11
	global_store_dwordx4 v230, v[8:11], s[22:23] offset:64
	v_cvt_pk_bf16_f32 v16, v16, v17
	v_cvt_pk_bf16_f32 v17, v18, v19
	v_cvt_pk_bf16_f32 v18, v20, v21
	v_cvt_pk_bf16_f32 v19, v22, v23
	s_nop 1
	v_permlane16_swap_b32_e32 v16, v18
	v_permlane16_swap_b32_e32 v17, v19
	global_store_dwordx4 v230, v[16:19], s[22:23] offset:128
	v_cvt_pk_bf16_f32 v24, v24, v25
	v_cvt_pk_bf16_f32 v25, v26, v27
	v_cvt_pk_bf16_f32 v26, v28, v29
	v_cvt_pk_bf16_f32 v27, v30, v31
	s_nop 1
	v_permlane16_swap_b32_e32 v24, v26
	v_permlane16_swap_b32_e32 v25, v27
	global_store_dwordx4 v230, v[24:27], s[22:23] offset:192
	v_cvt_pk_bf16_f32 v32, v32, v33
	v_cvt_pk_bf16_f32 v33, v34, v35
	v_cvt_pk_bf16_f32 v34, v36, v37
	v_cvt_pk_bf16_f32 v35, v38, v39
	s_nop 1
	v_permlane16_swap_b32_e32 v32, v34
	v_permlane16_swap_b32_e32 v33, v35
	global_store_dwordx4 v231, v[32:35], s[22:23]
	v_cvt_pk_bf16_f32 v40, v40, v41
	v_cvt_pk_bf16_f32 v41, v42, v43
	v_cvt_pk_bf16_f32 v42, v44, v45
	v_cvt_pk_bf16_f32 v43, v46, v47
	s_nop 1
	v_permlane16_swap_b32_e32 v40, v42
	v_permlane16_swap_b32_e32 v41, v43
	global_store_dwordx4 v231, v[40:43], s[22:23] offset:64
	v_cvt_pk_bf16_f32 v48, v48, v49
	v_cvt_pk_bf16_f32 v49, v50, v51
	v_cvt_pk_bf16_f32 v50, v52, v53
	v_cvt_pk_bf16_f32 v51, v54, v55
	s_nop 1
	v_permlane16_swap_b32_e32 v48, v50
	v_permlane16_swap_b32_e32 v49, v51
	global_store_dwordx4 v231, v[48:51], s[22:23] offset:128
	v_cvt_pk_bf16_f32 v56, v56, v57
	v_cvt_pk_bf16_f32 v57, v58, v59
	v_cvt_pk_bf16_f32 v58, v60, v61
	v_cvt_pk_bf16_f32 v59, v62, v63
	s_nop 1
	v_permlane16_swap_b32_e32 v56, v58
	v_permlane16_swap_b32_e32 v57, v59
	global_store_dwordx4 v231, v[56:59], s[22:23] offset:192
	v_cvt_pk_bf16_f32 v64, v64, v65
	v_cvt_pk_bf16_f32 v65, v66, v67
	v_cvt_pk_bf16_f32 v66, v68, v69
	v_cvt_pk_bf16_f32 v67, v70, v71
	s_nop 1
	v_permlane16_swap_b32_e32 v64, v66
	v_permlane16_swap_b32_e32 v65, v67
	global_store_dwordx4 v232, v[64:67], s[22:23]
	v_cvt_pk_bf16_f32 v72, v72, v73
	v_cvt_pk_bf16_f32 v73, v74, v75
	v_cvt_pk_bf16_f32 v74, v76, v77
	v_cvt_pk_bf16_f32 v75, v78, v79
	s_nop 1
	v_permlane16_swap_b32_e32 v72, v74
	v_permlane16_swap_b32_e32 v73, v75
	global_store_dwordx4 v232, v[72:75], s[22:23] offset:64
	v_cvt_pk_bf16_f32 v80, v80, v81
	v_cvt_pk_bf16_f32 v81, v82, v83
	v_cvt_pk_bf16_f32 v82, v84, v85
	v_cvt_pk_bf16_f32 v83, v86, v87
	s_nop 1
	v_permlane16_swap_b32_e32 v80, v82
	v_permlane16_swap_b32_e32 v81, v83
	global_store_dwordx4 v232, v[80:83], s[22:23] offset:128
	v_cvt_pk_bf16_f32 v88, v88, v89
	v_cvt_pk_bf16_f32 v89, v90, v91
	v_cvt_pk_bf16_f32 v90, v92, v93
	v_cvt_pk_bf16_f32 v91, v94, v95
	s_nop 1
	v_permlane16_swap_b32_e32 v88, v90
	v_permlane16_swap_b32_e32 v89, v91
	global_store_dwordx4 v232, v[88:91], s[22:23] offset:192
	v_cvt_pk_bf16_f32 v96, v96, v97
	v_cvt_pk_bf16_f32 v97, v98, v99
	v_cvt_pk_bf16_f32 v98, v100, v101
	v_cvt_pk_bf16_f32 v99, v102, v103
	s_nop 1
	v_permlane16_swap_b32_e32 v96, v98
	v_permlane16_swap_b32_e32 v97, v99
	global_store_dwordx4 v233, v[96:99], s[22:23]
	v_cvt_pk_bf16_f32 v104, v104, v105
	v_cvt_pk_bf16_f32 v105, v106, v107
	v_cvt_pk_bf16_f32 v106, v108, v109
	v_cvt_pk_bf16_f32 v107, v110, v111
	s_nop 1
	v_permlane16_swap_b32_e32 v104, v106
	v_permlane16_swap_b32_e32 v105, v107
	global_store_dwordx4 v233, v[104:107], s[22:23] offset:64
; template <int EPI> ...
;     ...
;         outb[(size_t)row * 1024 + c0] = f2bf(v0);
;         outb[(size_t)row * 1024 + c1] = f2bf(v1);
;         float s = hsum32(v0 * v0 + v1 * v1);
;         if ((lane & 31) == 0) part[(size_t)row * 16 + nt * 2 + wn] = s;
	v_cvt_pk_bf16_f32 v112, v112, v113
	v_cvt_pk_bf16_f32 v113, v114, v115
	v_cvt_pk_bf16_f32 v114, v116, v117
	v_cvt_pk_bf16_f32 v115, v118, v119
	s_nop 1
	v_permlane16_swap_b32_e32 v112, v114
	v_permlane16_swap_b32_e32 v113, v115
	global_store_dwordx4 v233, v[112:115], s[22:23] offset:128
	v_cvt_pk_bf16_f32 v120, v120, v121
	v_cvt_pk_bf16_f32 v121, v122, v123
	v_cvt_pk_bf16_f32 v122, v124, v125
	v_cvt_pk_bf16_f32 v123, v126, v127
	s_nop 1
	v_permlane16_swap_b32_e32 v120, v122
	v_permlane16_swap_b32_e32 v121, v123
	global_store_dwordx4 v233, v[120:123], s[22:23] offset:192
	v_mov_b32_e32 v238, v234
	v_mov_b32_e32 v239, v235
	v_mov_b32_e32 v240, v236
	v_mov_b32_e32 v241, v237
	s_nop 1
	v_permlane16_swap_b32_e32 v238, v234
	v_permlane16_swap_b32_e32 v239, v235
	v_permlane16_swap_b32_e32 v240, v236
	v_permlane16_swap_b32_e32 v241, v237
	v_add_f32_e32 v234, v234, v238
	v_add_f32_e32 v235, v235, v239
	v_add_f32_e32 v236, v236, v240
	v_add_f32_e32 v237, v237, v241
	v_mov_b32_e32 v238, v234
	v_mov_b32_e32 v239, v235
	v_mov_b32_e32 v240, v236
	v_mov_b32_e32 v241, v237
	s_nop 1
	v_permlane32_swap_b32_e32 v238, v234
	v_permlane32_swap_b32_e32 v239, v235
	v_permlane32_swap_b32_e32 v240, v236
	v_permlane32_swap_b32_e32 v241, v237
	v_add_f32_e32 v234, v234, v238
	v_add_f32_e32 v235, v235, v239
	v_add_f32_e32 v236, v236, v240
	v_add_f32_e32 v237, v237, v241
	v_mov_b32_e32 v238, v234
	v_mov_b32_e32 v239, 0
	global_store_dwordx2 v247, v[238:239], s[14:15]
	s_nop 1
	v_mov_b32_e32 v238, v235
	v_mov_b32_e32 v239, 0
	global_store_dwordx2 v247, v[238:239], s[14:15] offset:1024
	s_nop 1
	v_mov_b32_e32 v238, v236
	v_mov_b32_e32 v239, 0
	global_store_dwordx2 v247, v[238:239], s[14:15] offset:2048
	s_nop 1
	v_mov_b32_e32 v238, v237
	v_mov_b32_e32 v239, 0
	global_store_dwordx2 v247, v[238:239], s[14:15] offset:3072
	s_nop 1
	s_branch .Lgc_next
.Lgc_unitN:
	ds_read_b128 v[130:133], v226
	ds_read_b128 v[146:149], v228
	ds_read_b128 v[150:153], v228 offset:2048
	ds_read_b128 v[154:157], v228 offset:4096
	ds_read_b128 v[158:161], v228 offset:6144
	ds_read_b128 v[162:165], v228 offset:8192
	ds_read_b128 v[166:169], v228 offset:10240
	ds_read_b128 v[170:173], v228 offset:12288
	ds_read_b128 v[174:177], v228 offset:14336
	ds_read_b128 v[134:137], v226 offset:2048
	ds_read_b128 v[138:141], v226 offset:4096
	ds_read_b128 v[142:145], v226 offset:6144
	s_waitcnt lgkmcnt(3)
	v_mfma_f32_16x16x32_bf16 v[0:3], v[130:133], v[146:149], 0
	ds_read_b128 v[178:181], v227
	v_mfma_f32_16x16x32_bf16 v[4:7], v[130:133], v[150:153], 0
	ds_read_b128 v[194:197], v229
	v_mfma_f32_16x16x32_bf16 v[8:11], v[130:133], v[154:157], 0
	ds_read_b128 v[198:201], v229 offset:2048
	v_mfma_f32_16x16x32_bf16 v[12:15], v[130:133], v[158:161], 0
	ds_read_b128 v[202:205], v229 offset:4096
	v_mfma_f32_16x16x32_bf16 v[16:19], v[130:133], v[162:165], 0
	ds_read_b128 v[206:209], v229 offset:6144
	v_mfma_f32_16x16x32_bf16 v[20:23], v[130:133], v[166:169], 0
	ds_read_b128 v[210:213], v229 offset:8192
	v_mfma_f32_16x16x32_bf16 v[24:27], v[130:133], v[170:173], 0
	ds_read_b128 v[214:217], v229 offset:10240
	v_mfma_f32_16x16x32_bf16 v[28:31], v[130:133], v[174:177], 0
	ds_read_b128 v[218:221], v229 offset:12288
	s_waitcnt lgkmcnt(10)
	v_mfma_f32_16x16x32_bf16 v[32:35], v[134:137], v[146:149], 0
	ds_read_b128 v[222:225], v229 offset:14336
	v_mfma_f32_16x16x32_bf16 v[36:39], v[134:137], v[150:153], 0
	ds_read_b128 v[182:185], v227 offset:2048
	v_mfma_f32_16x16x32_bf16 v[40:43], v[134:137], v[154:157], 0
	ds_read_b128 v[186:189], v227 offset:4096
	v_mfma_f32_16x16x32_bf16 v[44:47], v[134:137], v[158:161], 0
	ds_read_b128 v[190:193], v227 offset:6144
	v_mfma_f32_16x16x32_bf16 v[48:51], v[134:137], v[162:165], 0
	v_add_u32_e32 v226, s31, v226
	v_mfma_f32_16x16x32_bf16 v[52:55], v[134:137], v[166:169], 0
	v_add_u32_e32 v227, s31, v227
	v_mfma_f32_16x16x32_bf16 v[56:59], v[134:137], v[170:173], 0
	v_add_u32_e32 v228, s31, v228
	v_mfma_f32_16x16x32_bf16 v[60:63], v[134:137], v[174:177], 0
	v_add_u32_e32 v229, s31, v229
	s_waitcnt lgkmcnt(13)
	v_mfma_f32_16x16x32_bf16 v[64:67], v[138:141], v[146:149], 0
	v_mfma_f32_16x16x32_bf16 v[68:71], v[138:141], v[150:153], 0
	v_mfma_f32_16x16x32_bf16 v[72:75], v[138:141], v[154:157], 0
	v_mfma_f32_16x16x32_bf16 v[76:79], v[138:141], v[158:161], 0
	v_mfma_f32_16x16x32_bf16 v[80:83], v[138:141], v[162:165], 0
	v_mfma_f32_16x16x32_bf16 v[84:87], v[138:141], v[166:169], 0
	v_mfma_f32_16x16x32_bf16 v[88:91], v[138:141], v[170:173], 0
	v_mfma_f32_16x16x32_bf16 v[92:95], v[138:141], v[174:177], 0
	s_waitcnt lgkmcnt(12)
	v_mfma_f32_16x16x32_bf16 v[96:99], v[142:145], v[146:149], 0
	v_mfma_f32_16x16x32_bf16 v[100:103], v[142:145], v[150:153], 0
	v_mfma_f32_16x16x32_bf16 v[104:107], v[142:145], v[154:157], 0
	v_mfma_f32_16x16x32_bf16 v[108:111], v[142:145], v[158:161], 0
	v_mfma_f32_16x16x32_bf16 v[112:115], v[142:145], v[162:165], 0
	v_mfma_f32_16x16x32_bf16 v[116:119], v[142:145], v[166:169], 0
	v_mfma_f32_16x16x32_bf16 v[120:123], v[142:145], v[170:173], 0
	v_mfma_f32_16x16x32_bf16 v[124:127], v[142:145], v[174:177], 0
	s_add_u32 s13, s13, 1
	s_cmp_eq_u32 s13, 3
	s_cselect_b32 s13, 0, s13
	s_cmp_eq_u32 s13, 2
	s_cselect_b32 s31, s34, s35
	s_waitcnt lgkmcnt(0)
	s_barrier
	s_cmp_eq_u32 s18, 0
	s_cbranch_scc1 .Lgc_tailN
; #define RAW_BARRIER() do { asm volatile("s_waitcnt lgkmcnt(0)" ::: "memory"); __builtin_amdgcn_s_barrier(); asm volatile("" ::: "memory"); } while (0)
; template <int EPI>
; __device__ __forceinline__ void gemm_phase(const Params& p, const u16* __restrict__ A, int lda, const u16* __restrict__ BT, int ldb,
;                            int K, int N, u16* __restrict__ outb, int ldo, int resid_in, int boff) {
;     ...
;     for (int kt = 0; kt < KT; kt += 2) {
;       if (kt + 1 < KT) WRITEY(1);
;       if (kt + 3 < KT) LOADY(kt + 3);
;       COMPUTE(0);
;       RAW_BARRIER();
;       if (kt + 1 >= KT) break;
;       if (kt + 2 < KT) WRITEX(0);
;       if (kt + 4 < KT) LOADX(kt + 4);
;       COMPUTE(1);
;       RAW_BARRIER();
;     }
.Lgc_loopN:
	v_mfma_f32_16x16x32_bf16 v[0:3], v[178:181], v[194:197], v[0:3]
	ds_read_b128 v[130:133], v226
	v_mfma_f32_16x16x32_bf16 v[4:7], v[178:181], v[198:201], v[4:7]
	ds_read_b128 v[146:149], v228
	v_mfma_f32_16x16x32_bf16 v[8:11], v[178:181], v[202:205], v[8:11]
	ds_read_b128 v[150:153], v228 offset:2048
	v_mfma_f32_16x16x32_bf16 v[12:15], v[178:181], v[206:209], v[12:15]
	ds_read_b128 v[154:157], v228 offset:4096
	v_mfma_f32_16x16x32_bf16 v[16:19], v[178:181], v[210:213], v[16:19]
	ds_read_b128 v[158:161], v228 offset:6144
	v_mfma_f32_16x16x32_bf16 v[20:23], v[178:181], v[214:217], v[20:23]
	ds_read_b128 v[162:165], v228 offset:8192
	v_mfma_f32_16x16x32_bf16 v[24:27], v[178:181], v[218:221], v[24:27]
	ds_read_b128 v[166:169], v228 offset:10240
	v_mfma_f32_16x16x32_bf16 v[28:31], v[178:181], v[222:225], v[28:31]
	ds_read_b128 v[170:173], v228 offset:12288
	v_mfma_f32_16x16x32_bf16 v[32:35], v[182:185], v[194:197], v[32:35]
	ds_read_b128 v[174:177], v228 offset:14336
	v_mfma_f32_16x16x32_bf16 v[36:39], v[182:185], v[198:201], v[36:39]
	ds_read_b128 v[134:137], v226 offset:2048
	v_mfma_f32_16x16x32_bf16 v[40:43], v[182:185], v[202:205], v[40:43]
	ds_read_b128 v[138:141], v226 offset:4096
	v_mfma_f32_16x16x32_bf16 v[44:47], v[182:185], v[206:209], v[44:47]
	ds_read_b128 v[142:145], v226 offset:6144
	v_mfma_f32_16x16x32_bf16 v[48:51], v[182:185], v[210:213], v[48:51]
	v_mfma_f32_16x16x32_bf16 v[52:55], v[182:185], v[214:217], v[52:55]
	v_mfma_f32_16x16x32_bf16 v[56:59], v[182:185], v[218:221], v[56:59]
	v_mfma_f32_16x16x32_bf16 v[60:63], v[182:185], v[222:225], v[60:63]
	v_mfma_f32_16x16x32_bf16 v[64:67], v[186:189], v[194:197], v[64:67]
	v_mfma_f32_16x16x32_bf16 v[68:71], v[186:189], v[198:201], v[68:71]
	v_mfma_f32_16x16x32_bf16 v[72:75], v[186:189], v[202:205], v[72:75]
	v_mfma_f32_16x16x32_bf16 v[76:79], v[186:189], v[206:209], v[76:79]
	v_mfma_f32_16x16x32_bf16 v[80:83], v[186:189], v[210:213], v[80:83]
	v_mfma_f32_16x16x32_bf16 v[84:87], v[186:189], v[214:217], v[84:87]
	v_mfma_f32_16x16x32_bf16 v[88:91], v[186:189], v[218:221], v[88:91]
	v_mfma_f32_16x16x32_bf16 v[92:95], v[186:189], v[222:225], v[92:95]
	v_mfma_f32_16x16x32_bf16 v[96:99], v[190:193], v[194:197], v[96:99]
	v_mfma_f32_16x16x32_bf16 v[100:103], v[190:193], v[198:201], v[100:103]
	v_mfma_f32_16x16x32_bf16 v[104:107], v[190:193], v[202:205], v[104:107]
	v_mfma_f32_16x16x32_bf16 v[108:111], v[190:193], v[206:209], v[108:111]
	v_mfma_f32_16x16x32_bf16 v[112:115], v[190:193], v[210:213], v[112:115]
	v_mfma_f32_16x16x32_bf16 v[116:119], v[190:193], v[214:217], v[116:119]
	v_mfma_f32_16x16x32_bf16 v[120:123], v[190:193], v[218:221], v[120:123]
	v_mfma_f32_16x16x32_bf16 v[124:127], v[190:193], v[222:225], v[124:127]
	s_waitcnt lgkmcnt(0)
	s_nop 0
	v_mfma_f32_16x16x32_bf16 v[0:3], v[130:133], v[146:149], v[0:3]
	ds_read_b128 v[178:181], v227
	v_mfma_f32_16x16x32_bf16 v[4:7], v[130:133], v[150:153], v[4:7]
	ds_read_b128 v[194:197], v229
	v_mfma_f32_16x16x32_bf16 v[8:11], v[130:133], v[154:157], v[8:11]
	ds_read_b128 v[198:201], v229 offset:2048
	v_mfma_f32_16x16x32_bf16 v[12:15], v[130:133], v[158:161], v[12:15]
	ds_read_b128 v[202:205], v229 offset:4096
	v_mfma_f32_16x16x32_bf16 v[16:19], v[130:133], v[162:165], v[16:19]
	ds_read_b128 v[206:209], v229 offset:6144
	v_mfma_f32_16x16x32_bf16 v[20:23], v[130:133], v[166:169], v[20:23]
	ds_read_b128 v[210:213], v229 offset:8192
	v_mfma_f32_16x16x32_bf16 v[24:27], v[130:133], v[170:173], v[24:27]
	ds_read_b128 v[214:217], v229 offset:10240
	v_mfma_f32_16x16x32_bf16 v[28:31], v[130:133], v[174:177], v[28:31]
	ds_read_b128 v[218:221], v229 offset:12288
	v_mfma_f32_16x16x32_bf16 v[32:35], v[134:137], v[146:149], v[32:35]
	ds_read_b128 v[222:225], v229 offset:14336
	v_mfma_f32_16x16x32_bf16 v[36:39], v[134:137], v[150:153], v[36:39]
	ds_read_b128 v[182:185], v227 offset:2048
	v_mfma_f32_16x16x32_bf16 v[40:43], v[134:137], v[154:157], v[40:43]
	ds_read_b128 v[186:189], v227 offset:4096
	v_mfma_f32_16x16x32_bf16 v[44:47], v[134:137], v[158:161], v[44:47]
	ds_read_b128 v[190:193], v227 offset:6144
	v_mfma_f32_16x16x32_bf16 v[48:51], v[134:137], v[162:165], v[48:51]
	v_add_u32_e32 v226, s31, v226
	v_mfma_f32_16x16x32_bf16 v[52:55], v[134:137], v[166:169], v[52:55]
	v_add_u32_e32 v227, s31, v227
	v_mfma_f32_16x16x32_bf16 v[56:59], v[134:137], v[170:173], v[56:59]
	v_add_u32_e32 v228, s31, v228
	v_mfma_f32_16x16x32_bf16 v[60:63], v[134:137], v[174:177], v[60:63]
	v_add_u32_e32 v229, s31, v229
	v_mfma_f32_16x16x32_bf16 v[64:67], v[138:141], v[146:149], v[64:67]
	v_mfma_f32_16x16x32_bf16 v[68:71], v[138:141], v[150:153], v[68:71]
	v_mfma_f32_16x16x32_bf16 v[72:75], v[138:141], v[154:157], v[72:75]
	v_mfma_f32_16x16x32_bf16 v[76:79], v[138:141], v[158:161], v[76:79]
	v_mfma_f32_16x16x32_bf16 v[80:83], v[138:141], v[162:165], v[80:83]
	v_mfma_f32_16x16x32_bf16 v[84:87], v[138:141], v[166:169], v[84:87]
	v_mfma_f32_16x16x32_bf16 v[88:91], v[138:141], v[170:173], v[88:91]
	v_mfma_f32_16x16x32_bf16 v[92:95], v[138:141], v[174:177], v[92:95]
	v_mfma_f32_16x16x32_bf16 v[96:99], v[142:145], v[146:149], v[96:99]
	v_mfma_f32_16x16x32_bf16 v[100:103], v[142:145], v[150:153], v[100:103]
	v_mfma_f32_16x16x32_bf16 v[104:107], v[142:145], v[154:157], v[104:107]
	v_mfma_f32_16x16x32_bf16 v[108:111], v[142:145], v[158:161], v[108:111]
	v_mfma_f32_16x16x32_bf16 v[112:115], v[142:145], v[162:165], v[112:115]
	v_mfma_f32_16x16x32_bf16 v[116:119], v[142:145], v[166:169], v[116:119]
	v_mfma_f32_16x16x32_bf16 v[120:123], v[142:145], v[170:173], v[120:123]
	v_mfma_f32_16x16x32_bf16 v[124:127], v[142:145], v[174:177], v[124:127]
	s_add_u32 s13, s13, 1
	s_cmp_eq_u32 s13, 3
	s_cselect_b32 s13, 0, s13
	s_cmp_eq_u32 s13, 2
	s_cselect_b32 s31, s34, s35
	s_waitcnt lgkmcnt(0)
	s_barrier
	s_sub_u32 s18, s18, 1
	s_cmp_lg_u32 s18, 0
	s_cbranch_scc1 .Lgc_loopN
; template <int EPI>
; __device__ __forceinline__ void gemm_phase(const Params& p, const u16* __restrict__ A, int lda, const u16* __restrict__ BT, int ldb,
;                            int K, int N, u16* __restrict__ outb, int ldo, int resid_in, int boff) {
;     ...
;     if (EPI == EPI_RES && part_unit) {
;       float* xfp = p.out;
; #pragma unroll
;       for (int i = 0; i < 16; i++) {
;         const int rl = wm * 64 + 4 * (lane >> 5) + (i & 3) + 8 * (i >> 2);
;         float* r0p = xfp + (size_t)(m0 + rl) * 1024;
;         float* r1p = r0p + (size_t)32 * 1024;
;         atomicAdd(r0p + c0, acc00[i]); atomicAdd(r0p + c1, acc01[i]);
;         atomicAdd(r1p + c0, acc10[i]); atomicAdd(r1p + c1, acc11[i]);
;       }
.Lgc_tailN:
	v_mfma_f32_16x16x32_bf16 v[0:3], v[178:181], v[194:197], v[0:3]
	v_mfma_f32_16x16x32_bf16 v[4:7], v[178:181], v[198:201], v[4:7]
	v_mfma_f32_16x16x32_bf16 v[8:11], v[178:181], v[202:205], v[8:11]
	v_mfma_f32_16x16x32_bf16 v[12:15], v[178:181], v[206:209], v[12:15]
	v_mfma_f32_16x16x32_bf16 v[16:19], v[178:181], v[210:213], v[16:19]
	v_mfma_f32_16x16x32_bf16 v[20:23], v[178:181], v[214:217], v[20:23]
	v_mfma_f32_16x16x32_bf16 v[24:27], v[178:181], v[218:221], v[24:27]
	v_mfma_f32_16x16x32_bf16 v[28:31], v[178:181], v[222:225], v[28:31]
	v_mfma_f32_16x16x32_bf16 v[32:35], v[182:185], v[194:197], v[32:35]
	v_mfma_f32_16x16x32_bf16 v[36:39], v[182:185], v[198:201], v[36:39]
	v_mfma_f32_16x16x32_bf16 v[40:43], v[182:185], v[202:205], v[40:43]
	v_mfma_f32_16x16x32_bf16 v[44:47], v[182:185], v[206:209], v[44:47]
	v_mfma_f32_16x16x32_bf16 v[48:51], v[182:185], v[210:213], v[48:51]
	v_mfma_f32_16x16x32_bf16 v[52:55], v[182:185], v[214:217], v[52:55]
	v_mfma_f32_16x16x32_bf16 v[56:59], v[182:185], v[218:221], v[56:59]
	v_mfma_f32_16x16x32_bf16 v[60:63], v[182:185], v[222:225], v[60:63]
	v_mfma_f32_16x16x32_bf16 v[64:67], v[186:189], v[194:197], v[64:67]
	v_mfma_f32_16x16x32_bf16 v[68:71], v[186:189], v[198:201], v[68:71]
	v_mfma_f32_16x16x32_bf16 v[72:75], v[186:189], v[202:205], v[72:75]
	v_mfma_f32_16x16x32_bf16 v[76:79], v[186:189], v[206:209], v[76:79]
	v_mfma_f32_16x16x32_bf16 v[80:83], v[186:189], v[210:213], v[80:83]
	v_mfma_f32_16x16x32_bf16 v[84:87], v[186:189], v[214:217], v[84:87]
	v_mfma_f32_16x16x32_bf16 v[88:91], v[186:189], v[218:221], v[88:91]
	v_mfma_f32_16x16x32_bf16 v[92:95], v[186:189], v[222:225], v[92:95]
	v_mfma_f32_16x16x32_bf16 v[96:99], v[190:193], v[194:197], v[96:99]
	v_mfma_f32_16x16x32_bf16 v[100:103], v[190:193], v[198:201], v[100:103]
	v_mfma_f32_16x16x32_bf16 v[104:107], v[190:193], v[202:205], v[104:107]
	v_mfma_f32_16x16x32_bf16 v[108:111], v[190:193], v[206:209], v[108:111]
	v_mfma_f32_16x16x32_bf16 v[112:115], v[190:193], v[210:213], v[112:115]
	v_mfma_f32_16x16x32_bf16 v[116:119], v[190:193], v[214:217], v[116:119]
	v_mfma_f32_16x16x32_bf16 v[120:123], v[190:193], v[218:221], v[120:123]
	v_mfma_f32_16x16x32_bf16 v[124:127], v[190:193], v[222:225], v[124:127]
	s_lshl_b32 s11, s6, 8
	s_lshl_b32 s12, s4, 6
	s_add_u32 s11, s11, s12
	v_add_u32_e32 v238, s11, v248
	v_sub_u32_e32 v238, v238, v248
	v_lshl_add_u32 v238, v249, 2, v238
	v_lshlrev_b32_e32 v243, 12, v238
	s_lshl_b32 s11, s7, 7
	v_add_u32_e32 v239, s11, v248
	v_lshlrev_b32_e32 v239, 2, v239
	v_add_u32_e32 v243, v243, v239
	s_nop 7
	s_mov_b32 s36, s94
	s_mov_b32 s37, s95
	global_atomic_add_f32 v243, v0, s[36:37]
	global_atomic_add_f32 v243, v4, s[36:37] offset:64
	global_atomic_add_f32 v243, v8, s[36:37] offset:128
	global_atomic_add_f32 v243, v12, s[36:37] offset:192
	global_atomic_add_f32 v243, v16, s[36:37] offset:256
	global_atomic_add_f32 v243, v20, s[36:37] offset:320
	global_atomic_add_f32 v243, v24, s[36:37] offset:384
	global_atomic_add_f32 v243, v28, s[36:37] offset:448
	s_add_u32 s36, s36, 0x1000
	s_addc_u32 s37, s37, 0
	global_atomic_add_f32 v243, v1, s[36:37]
	global_atomic_add_f32 v243, v5, s[36:37] offset:64
	global_atomic_add_f32 v243, v9, s[36:37] offset:128
	global_atomic_add_f32 v243, v13, s[36:37] offset:192
	global_atomic_add_f32 v243, v17, s[36:37] offset:256
	global_atomic_add_f32 v243, v21, s[36:37] offset:320
	global_atomic_add_f32 v243, v25, s[36:37] offset:384
	global_atomic_add_f32 v243, v29, s[36:37] offset:448
	s_add_u32 s36, s36, 0x1000
	s_addc_u32 s37, s37, 0
	global_atomic_add_f32 v243, v2, s[36:37]
	global_atomic_add_f32 v243, v6, s[36:37] offset:64
	global_atomic_add_f32 v243, v10, s[36:37] offset:128
	global_atomic_add_f32 v243, v14, s[36:37] offset:192
	global_atomic_add_f32 v243, v18, s[36:37] offset:256
	global_atomic_add_f32 v243, v22, s[36:37] offset:320
	global_atomic_add_f32 v243, v26, s[36:37] offset:384
	global_atomic_add_f32 v243, v30, s[36:37] offset:448
	s_add_u32 s36, s36, 0x1000
	s_addc_u32 s37, s37, 0
	global_atomic_add_f32 v243, v3, s[36:37]
	global_atomic_add_f32 v243, v7, s[36:37] offset:64
	global_atomic_add_f32 v243, v11, s[36:37] offset:128
	global_atomic_add_f32 v243, v15, s[36:37] offset:192
	global_atomic_add_f32 v243, v19, s[36:37] offset:256
	global_atomic_add_f32 v243, v23, s[36:37] offset:320
	global_atomic_add_f32 v243, v27, s[36:37] offset:384
	global_atomic_add_f32 v243, v31, s[36:37] offset:448
	s_add_u32 s36, s36, 0xd000
	s_addc_u32 s37, s37, 0
	global_atomic_add_f32 v243, v32, s[36:37]
	global_atomic_add_f32 v243, v36, s[36:37] offset:64
	global_atomic_add_f32 v243, v40, s[36:37] offset:128
	global_atomic_add_f32 v243, v44, s[36:37] offset:192
	global_atomic_add_f32 v243, v48, s[36:37] offset:256
	global_atomic_add_f32 v243, v52, s[36:37] offset:320
	global_atomic_add_f32 v243, v56, s[36:37] offset:384
	global_atomic_add_f32 v243, v60, s[36:37] offset:448
	s_add_u32 s36, s36, 0x1000
	s_addc_u32 s37, s37, 0
	global_atomic_add_f32 v243, v33, s[36:37]
	global_atomic_add_f32 v243, v37, s[36:37] offset:64
; template <int EPI>
; __device__ __forceinline__ void gemm_phase(const Params& p, const u16* __restrict__ A, int lda, const u16* __restrict__ BT, int ldb,
;                            int K, int N, u16* __restrict__ outb, int ldo, int resid_in, int boff) {
;     ...
;     if (EPI == EPI_RES && part_unit) {
;       float* xfp = p.out;
; #pragma unroll
;       for (int i = 0; i < 16; i++) {
;         const int rl = wm * 64 + 4 * (lane >> 5) + (i & 3) + 8 * (i >> 2);
;         float* r0p = xfp + (size_t)(m0 + rl) * 1024;
;         float* r1p = r0p + (size_t)32 * 1024;
;         atomicAdd(r0p + c0, acc00[i]); atomicAdd(r0p + c1, acc01[i]);
;         atomicAdd(r1p + c0, acc10[i]); atomicAdd(r1p + c1, acc11[i]);
;       }
	global_atomic_add_f32 v243, v41, s[36:37] offset:128
	global_atomic_add_f32 v243, v45, s[36:37] offset:192
	global_atomic_add_f32 v243, v49, s[36:37] offset:256
	global_atomic_add_f32 v243, v53, s[36:37] offset:320
	global_atomic_add_f32 v243, v57, s[36:37] offset:384
	global_atomic_add_f32 v243, v61, s[36:37] offset:448
	s_add_u32 s36, s36, 0x1000
	s_addc_u32 s37, s37, 0
	global_atomic_add_f32 v243, v34, s[36:37]
	global_atomic_add_f32 v243, v38, s[36:37] offset:64
	global_atomic_add_f32 v243, v42, s[36:37] offset:128
	global_atomic_add_f32 v243, v46, s[36:37] offset:192
	global_atomic_add_f32 v243, v50, s[36:37] offset:256
	global_atomic_add_f32 v243, v54, s[36:37] offset:320
	global_atomic_add_f32 v243, v58, s[36:37] offset:384
	global_atomic_add_f32 v243, v62, s[36:37] offset:448
	s_add_u32 s36, s36, 0x1000
	s_addc_u32 s37, s37, 0
	global_atomic_add_f32 v243, v35, s[36:37]
	global_atomic_add_f32 v243, v39, s[36:37] offset:64
	global_atomic_add_f32 v243, v43, s[36:37] offset:128
	global_atomic_add_f32 v243, v47, s[36:37] offset:192
	global_atomic_add_f32 v243, v51, s[36:37] offset:256
	global_atomic_add_f32 v243, v55, s[36:37] offset:320
	global_atomic_add_f32 v243, v59, s[36:37] offset:384
	global_atomic_add_f32 v243, v63, s[36:37] offset:448
	s_add_u32 s36, s36, 0xd000
	s_addc_u32 s37, s37, 0
	global_atomic_add_f32 v243, v64, s[36:37]
	global_atomic_add_f32 v243, v68, s[36:37] offset:64
	global_atomic_add_f32 v243, v72, s[36:37] offset:128
	global_atomic_add_f32 v243, v76, s[36:37] offset:192
	global_atomic_add_f32 v243, v80, s[36:37] offset:256
	global_atomic_add_f32 v243, v84, s[36:37] offset:320
	global_atomic_add_f32 v243, v88, s[36:37] offset:384
	global_atomic_add_f32 v243, v92, s[36:37] offset:448
	s_add_u32 s36, s36, 0x1000
	s_addc_u32 s37, s37, 0
	global_atomic_add_f32 v243, v65, s[36:37]
	global_atomic_add_f32 v243, v69, s[36:37] offset:64
	global_atomic_add_f32 v243, v73, s[36:37] offset:128
	global_atomic_add_f32 v243, v77, s[36:37] offset:192
	global_atomic_add_f32 v243, v81, s[36:37] offset:256
	global_atomic_add_f32 v243, v85, s[36:37] offset:320
	global_atomic_add_f32 v243, v89, s[36:37] offset:384
	global_atomic_add_f32 v243, v93, s[36:37] offset:448
	s_add_u32 s36, s36, 0x1000
	s_addc_u32 s37, s37, 0
	global_atomic_add_f32 v243, v66, s[36:37]
	global_atomic_add_f32 v243, v70, s[36:37] offset:64
	global_atomic_add_f32 v243, v74, s[36:37] offset:128
	global_atomic_add_f32 v243, v78, s[36:37] offset:192
	global_atomic_add_f32 v243, v82, s[36:37] offset:256
	global_atomic_add_f32 v243, v86, s[36:37] offset:320
	global_atomic_add_f32 v243, v90, s[36:37] offset:384
	global_atomic_add_f32 v243, v94, s[36:37] offset:448
	s_add_u32 s36, s36, 0x1000
	s_addc_u32 s37, s37, 0
	global_atomic_add_f32 v243, v67, s[36:37]
	global_atomic_add_f32 v243, v71, s[36:37] offset:64
	global_atomic_add_f32 v243, v75, s[36:37] offset:128
	global_atomic_add_f32 v243, v79, s[36:37] offset:192
	global_atomic_add_f32 v243, v83, s[36:37] offset:256
	global_atomic_add_f32 v243, v87, s[36:37] offset:320
	global_atomic_add_f32 v243, v91, s[36:37] offset:384
	global_atomic_add_f32 v243, v95, s[36:37] offset:448
	s_add_u32 s36, s36, 0xd000
	s_addc_u32 s37, s37, 0
	global_atomic_add_f32 v243, v96, s[36:37]
	global_atomic_add_f32 v243, v100, s[36:37] offset:64
	global_atomic_add_f32 v243, v104, s[36:37] offset:128
	global_atomic_add_f32 v243, v108, s[36:37] offset:192
	global_atomic_add_f32 v243, v112, s[36:37] offset:256
	global_atomic_add_f32 v243, v116, s[36:37] offset:320
	global_atomic_add_f32 v243, v120, s[36:37] offset:384
	global_atomic_add_f32 v243, v124, s[36:37] offset:448
	s_add_u32 s36, s36, 0x1000
	s_addc_u32 s37, s37, 0
	global_atomic_add_f32 v243, v97, s[36:37]
	global_atomic_add_f32 v243, v101, s[36:37] offset:64
	global_atomic_add_f32 v243, v105, s[36:37] offset:128
	global_atomic_add_f32 v243, v109, s[36:37] offset:192
	global_atomic_add_f32 v243, v113, s[36:37] offset:256
	global_atomic_add_f32 v243, v117, s[36:37] offset:320
	global_atomic_add_f32 v243, v121, s[36:37] offset:384
	global_atomic_add_f32 v243, v125, s[36:37] offset:448
	s_add_u32 s36, s36, 0x1000
	s_addc_u32 s37, s37, 0
	global_atomic_add_f32 v243, v98, s[36:37]
	global_atomic_add_f32 v243, v102, s[36:37] offset:64
	global_atomic_add_f32 v243, v106, s[36:37] offset:128
	global_atomic_add_f32 v243, v110, s[36:37] offset:192
	global_atomic_add_f32 v243, v114, s[36:37] offset:256
	global_atomic_add_f32 v243, v118, s[36:37] offset:320
	global_atomic_add_f32 v243, v122, s[36:37] offset:384
	global_atomic_add_f32 v243, v126, s[36:37] offset:448
	s_add_u32 s36, s36, 0x1000
	s_addc_u32 s37, s37, 0
	global_atomic_add_f32 v243, v99, s[36:37]
	global_atomic_add_f32 v243, v103, s[36:37] offset:64
	global_atomic_add_f32 v243, v107, s[36:37] offset:128
	global_atomic_add_f32 v243, v111, s[36:37] offset:192
	global_atomic_add_f32 v243, v115, s[36:37] offset:256
	global_atomic_add_f32 v243, v119, s[36:37] offset:320
	global_atomic_add_f32 v243, v123, s[36:37] offset:384
	global_atomic_add_f32 v243, v127, s[36:37] offset:448
	s_nop 3
